# v047 + C-item QK fragment prefetch (two spare quads) + batched LDS read-back in the in-proj epilogue + next-iteration load prefetch in the final RMSNorm loop
# speedup vs baseline: 1.0020x; 1.0001x over previous
; template <int EPI>
; DI void gemm_tile(const Params& p, int layer, int mt, int nt, u16* sm, int wv) {
;     ...
;   if (EPI == 0) {
;     const float* ssl = p.ss + (size_t)layer * MTOK;
;     __syncthreads();
;     u16* stg = sm + (wm * 2 + wn) * (128 * LSTR);
;     if (!vtile) {
;       const float qsc = (nt < 2) ? 0.17677669529663687f * LOG2E
;                         : ((nt >= 8 && nt < 12) || nt == 18 || nt == 19) ? 0.125f * LOG2E : 1.f;
; #pragma unroll
;       for (int i = 0; i < 8; ++i) {
;         const int m = m0 + wm * 128 + 16 * i + fr;
;         const float rs = __builtin_amdgcn_rsqf(ssl[m] * (1.f / DM) + EPS) * qsc;
;         u16* d = stg + (16 * i + fr) * LSTR + 4 * fq;
; #pragma unroll
;         for (int j = 0; j < 4; ++j) {
;           u32x2 v = {pk2(acc[i][j][0] * rs, acc[i][j][1] * rs), pk2(acc[i][j][2] * rs, acc[i][j][3] * rs)};
;           *(u32x2*)(d + 16 * j) = v;
;         }
;       }
.LBB0_124:
	s_waitcnt vmcnt(8)
	v_mbcnt_lo_u32_b32 v138, -1, 0
	v_mbcnt_hi_u32_b32 v138, -1, v138
	s_lshl_b32 s21, s21, 8
	v_add_u32_e32 v0, s33, v138
	v_bfe_u32 v130, v0, 6, 21
	s_waitcnt vmcnt(7)
	v_mul_u32_u24_e32 v135, 0x4800, v130
	v_and_b32_e32 v130, 0xffffff80, v0
	v_and_b32_e32 v137, 15, v138
	v_bfe_u32 v134, v138, 4, 2
	v_bfe_u32 v131, v0, 6, 1
	s_mov_b64 s[6:7], -1
	s_andn2_b64 vcc, exec, s[4:5]
	v_add_u32_e32 v139, s21, v130
	v_lshlrev_b32_e32 v136, 4, v138
	s_barrier
	s_cbranch_vccnz .LBB0_126
	v_or_b32_e32 v132, v139, v137
	v_ashrrev_i32_e32 v133, 31, v132
	v_lshl_add_u64 v[132:133], v[132:133], 2, s[0:1]
	global_load_dword v142, v[132:133], off
	global_load_dword v150, v[132:133], off offset:64
	global_load_dword v151, v[132:133], off offset:128
	global_load_dword v152, v[132:133], off offset:192
	global_load_dword v153, v[132:133], off offset:256
	global_load_dword v154, v[132:133], off offset:320
	global_load_dword v155, v[132:133], off offset:384
	global_load_dword v156, v[132:133], off offset:448
	s_and_b32 s4, s20, 0x7ffffffc
	s_cmp_eq_u32 s4, 8
	s_cselect_b64 s[4:5], -1, 0
	s_and_b32 s6, s18, -16
	s_cmpk_eq_i32 s6, 0x90
	s_cselect_b64 s[6:7], -1, 0
	s_or_b64 vcc, s[6:7], s[4:5]
	s_cmp_gt_i32 s20, 1
	v_cndmask_b32_e32 v0, 1.0, v191, vcc
	s_cselect_b64 vcc, -1, 0
	v_cndmask_b32_e32 v0, v192, v0, vcc
	s_waitcnt vmcnt(7)
	v_mul_u32_u24_e32 v143, 0x90, v137
	v_lshlrev_b32_e32 v141, 3, v134
	v_add3_u32 v141, v135, v141, v143
	v_and_b32_e32 v140, 63, v138
	s_mov_b64 s[6:7], 0
	s_waitcnt vmcnt(0)
	v_fmamk_f32 v142, v142, 0x3a800000, v188
	v_rsq_f32_e32 v142, v142
	s_nop 0
	v_mul_f32_e32 v142, v0, v142
	v_mul_f32_e32 v144, v126, v142
	v_mul_f32_e32 v145, v127, v142
	v_mul_f32_e32 v146, v128, v142
	v_mul_f32_e32 v147, v129, v142
	v_cvt_pk_bf16_f32 v144, v144, v145
	v_cvt_pk_bf16_f32 v145, v146, v147
	v_mul_f32_e32 v146, v122, v142
	v_mul_f32_e32 v147, v123, v142
	v_mul_f32_e32 v148, v124, v142
	v_mul_f32_e32 v149, v125, v142
	v_cvt_pk_bf16_f32 v146, v146, v147
	v_cvt_pk_bf16_f32 v147, v148, v149
	ds_write2_b64 v141, v[144:145], v[146:147] offset1:4
	v_mul_f32_e32 v144, v118, v142
	v_mul_f32_e32 v145, v119, v142
	v_mul_f32_e32 v146, v120, v142
	v_mul_f32_e32 v147, v121, v142
	v_cvt_pk_bf16_f32 v144, v144, v145
	v_cvt_pk_bf16_f32 v145, v146, v147
	v_mul_f32_e32 v146, v114, v142
	v_mul_f32_e32 v147, v115, v142
	v_mul_f32_e32 v143, v117, v142
	v_mul_f32_e32 v142, v116, v142
	v_cvt_pk_bf16_f32 v146, v146, v147
	v_cvt_pk_bf16_f32 v147, v142, v143
	v_mov_b32_e32 v142, v150
	ds_write2_b64 v141, v[144:145], v[146:147] offset0:8 offset1:12
	s_waitcnt vmcnt(0)
	v_fmamk_f32 v142, v142, 0x3a800000, v188
	v_rsq_f32_e32 v142, v142
	s_nop 0
	v_mul_f32_e32 v142, v0, v142
	v_mul_f32_e32 v144, v110, v142
	v_mul_f32_e32 v145, v111, v142
	v_mul_f32_e32 v146, v112, v142
	v_mul_f32_e32 v147, v113, v142
	v_cvt_pk_bf16_f32 v144, v144, v145
	v_cvt_pk_bf16_f32 v145, v146, v147
	v_mul_f32_e32 v146, v106, v142
	v_mul_f32_e32 v147, v107, v142
	v_mul_f32_e32 v148, v108, v142
	v_mul_f32_e32 v149, v109, v142
	v_cvt_pk_bf16_f32 v146, v146, v147
	v_cvt_pk_bf16_f32 v147, v148, v149
	v_add_u32_e32 v148, 0x800, v141
	ds_write2_b64 v148, v[144:145], v[146:147] offset0:32 offset1:36
	v_mul_f32_e32 v144, v102, v142
	v_mul_f32_e32 v145, v103, v142
	v_mul_f32_e32 v146, v104, v142
	v_mul_f32_e32 v147, v105, v142
	v_cvt_pk_bf16_f32 v144, v144, v145
	v_cvt_pk_bf16_f32 v145, v146, v147
	v_mul_f32_e32 v146, v98, v142
	v_mul_f32_e32 v147, v99, v142
	v_mul_f32_e32 v143, v101, v142
	v_mul_f32_e32 v142, v100, v142
	v_cvt_pk_bf16_f32 v146, v146, v147
	v_cvt_pk_bf16_f32 v147, v142, v143
	v_mov_b32_e32 v142, v151
	ds_write2_b64 v148, v[144:145], v[146:147] offset0:40 offset1:44
	s_waitcnt vmcnt(0)
	v_fmamk_f32 v142, v142, 0x3a800000, v188
	v_rsq_f32_e32 v142, v142
	s_nop 0
	v_mul_f32_e32 v142, v0, v142
	v_mul_f32_e32 v144, v94, v142
	v_mul_f32_e32 v145, v95, v142
	v_mul_f32_e32 v146, v96, v142
	v_mul_f32_e32 v147, v97, v142
	v_cvt_pk_bf16_f32 v144, v144, v145
	v_cvt_pk_bf16_f32 v145, v146, v147
	v_mul_f32_e32 v146, v90, v142
	v_mul_f32_e32 v147, v91, v142
	v_mul_f32_e32 v148, v92, v142
	v_mul_f32_e32 v149, v93, v142
	v_cvt_pk_bf16_f32 v146, v146, v147
	v_cvt_pk_bf16_f32 v147, v148, v149
	v_add_u32_e32 v148, 0x1000, v141
	ds_write2_b64 v148, v[144:145], v[146:147] offset0:64 offset1:68
	v_mul_f32_e32 v144, v86, v142
	v_mul_f32_e32 v145, v87, v142
	v_mul_f32_e32 v146, v88, v142
	v_mul_f32_e32 v147, v89, v142
	v_cvt_pk_bf16_f32 v144, v144, v145
	v_cvt_pk_bf16_f32 v145, v146, v147
	v_mul_f32_e32 v146, v82, v142
	v_mul_f32_e32 v147, v83, v142
	v_mul_f32_e32 v143, v85, v142
	v_mul_f32_e32 v142, v84, v142
	v_cvt_pk_bf16_f32 v146, v146, v147
	v_cvt_pk_bf16_f32 v147, v142, v143
	v_mov_b32_e32 v142, v152
	ds_write2_b64 v148, v[144:145], v[146:147] offset0:72 offset1:76
	s_waitcnt vmcnt(0)
	v_fmamk_f32 v142, v142, 0x3a800000, v188
	v_rsq_f32_e32 v142, v142
	s_nop 0
	v_mul_f32_e32 v142, v0, v142
	v_mul_f32_e32 v144, v78, v142
	v_mul_f32_e32 v145, v79, v142
	v_mul_f32_e32 v146, v80, v142
	v_mul_f32_e32 v147, v81, v142
	v_cvt_pk_bf16_f32 v144, v144, v145
	v_cvt_pk_bf16_f32 v145, v146, v147
	v_mul_f32_e32 v146, v74, v142
	v_mul_f32_e32 v147, v75, v142
	v_mul_f32_e32 v148, v76, v142
	v_mul_f32_e32 v149, v77, v142
	v_cvt_pk_bf16_f32 v146, v146, v147
	v_cvt_pk_bf16_f32 v147, v148, v149
	v_add_u32_e32 v148, 0x1800, v141
	ds_write2_b64 v148, v[144:145], v[146:147] offset0:96 offset1:100
	v_mul_f32_e32 v144, v70, v142
	v_mul_f32_e32 v145, v71, v142
	v_mul_f32_e32 v146, v72, v142
	v_mul_f32_e32 v147, v73, v142
	v_cvt_pk_bf16_f32 v144, v144, v145
	v_cvt_pk_bf16_f32 v145, v146, v147
	v_mul_f32_e32 v146, v66, v142
	v_mul_f32_e32 v147, v67, v142
	v_mul_f32_e32 v143, v69, v142
	v_mul_f32_e32 v142, v68, v142
	v_cvt_pk_bf16_f32 v146, v146, v147
	v_cvt_pk_bf16_f32 v147, v142, v143
	v_mov_b32_e32 v142, v153
	ds_write2_b64 v148, v[144:145], v[146:147] offset0:104 offset1:108
	s_waitcnt vmcnt(0)
; template <int EPI>
; DI void gemm_tile(const Params& p, int layer, int mt, int nt, u16* sm, int wv) {
;     ...
; #pragma unroll
;       for (int i = 0; i < 8; ++i) {
;         const int m = m0 + wm * 128 + 16 * i + fr;
;         const float rs = __builtin_amdgcn_rsqf(ssl[m] * (1.f / DM) + EPS) * qsc;
;         u16* d = stg + (16 * i + fr) * LSTR + 4 * fq;
; #pragma unroll
;         for (int j = 0; j < 4; ++j) {
;           u32x2 v = {pk2(acc[i][j][0] * rs, acc[i][j][1] * rs), pk2(acc[i][j][2] * rs, acc[i][j][3] * rs)};
;           *(u32x2*)(d + 16 * j) = v;
;         }
;       }
;       u16* gdst = p.proj + (size_t)(m0 + wm * 128) * DIN + n0 + wn * 64;
; #pragma unroll
;       for (int t = 0; t < 16; ++t) {
;         const int c = lane + 64 * t, row = c >> 3, kc = c & 7;
;         const u32x4 v = *(const u32x4*)(stg + row * LSTR + kc * 8);
;         *(u32x4*)(gdst + (size_t)row * DIN + kc * 8) = v;
;       }
	v_fmamk_f32 v142, v142, 0x3a800000, v188
	v_rsq_f32_e32 v142, v142
	s_nop 0
	v_mul_f32_e32 v142, v0, v142
	v_mul_f32_e32 v144, v62, v142
	v_mul_f32_e32 v145, v63, v142
	v_mul_f32_e32 v146, v64, v142
	v_mul_f32_e32 v147, v65, v142
	v_cvt_pk_bf16_f32 v144, v144, v145
	v_cvt_pk_bf16_f32 v145, v146, v147
	v_mul_f32_e32 v146, v58, v142
	v_mul_f32_e32 v147, v59, v142
	v_mul_f32_e32 v148, v60, v142
	v_mul_f32_e32 v149, v61, v142
	v_cvt_pk_bf16_f32 v146, v146, v147
	v_cvt_pk_bf16_f32 v147, v148, v149
	v_add_u32_e32 v148, 0x2000, v141
	ds_write2_b64 v148, v[144:145], v[146:147] offset0:128 offset1:132
	v_mul_f32_e32 v144, v54, v142
	v_mul_f32_e32 v145, v55, v142
	v_mul_f32_e32 v146, v56, v142
	v_mul_f32_e32 v147, v57, v142
	v_cvt_pk_bf16_f32 v144, v144, v145
	v_cvt_pk_bf16_f32 v145, v146, v147
	v_mul_f32_e32 v146, v50, v142
	v_mul_f32_e32 v147, v51, v142
	v_mul_f32_e32 v143, v53, v142
	v_mul_f32_e32 v142, v52, v142
	v_cvt_pk_bf16_f32 v146, v146, v147
	v_cvt_pk_bf16_f32 v147, v142, v143
	v_mov_b32_e32 v142, v154
	ds_write2_b64 v148, v[144:145], v[146:147] offset0:136 offset1:140
	s_waitcnt vmcnt(0)
	v_fmamk_f32 v142, v142, 0x3a800000, v188
	v_rsq_f32_e32 v142, v142
	s_nop 0
	v_mul_f32_e32 v142, v0, v142
	v_mul_f32_e32 v144, v46, v142
	v_mul_f32_e32 v145, v47, v142
	v_mul_f32_e32 v146, v48, v142
	v_mul_f32_e32 v147, v49, v142
	v_cvt_pk_bf16_f32 v144, v144, v145
	v_cvt_pk_bf16_f32 v145, v146, v147
	v_mul_f32_e32 v146, v42, v142
	v_mul_f32_e32 v147, v43, v142
	v_mul_f32_e32 v148, v44, v142
	v_mul_f32_e32 v149, v45, v142
	v_cvt_pk_bf16_f32 v146, v146, v147
	v_cvt_pk_bf16_f32 v147, v148, v149
	v_add_u32_e32 v148, 0x2800, v141
	ds_write2_b64 v148, v[144:145], v[146:147] offset0:160 offset1:164
	v_mul_f32_e32 v144, v38, v142
	v_mul_f32_e32 v145, v39, v142
	v_mul_f32_e32 v146, v40, v142
	v_mul_f32_e32 v147, v41, v142
	v_cvt_pk_bf16_f32 v144, v144, v145
	v_cvt_pk_bf16_f32 v145, v146, v147
	v_mul_f32_e32 v146, v34, v142
	v_mul_f32_e32 v147, v35, v142
	v_mul_f32_e32 v143, v37, v142
	v_mul_f32_e32 v142, v36, v142
	v_cvt_pk_bf16_f32 v146, v146, v147
	v_cvt_pk_bf16_f32 v147, v142, v143
	v_mov_b32_e32 v142, v155
	ds_write2_b64 v148, v[144:145], v[146:147] offset0:168 offset1:172
	v_mov_b32_e32 v132, v156
	s_waitcnt vmcnt(1)
	v_fmamk_f32 v142, v142, 0x3a800000, v188
	v_rsq_f32_e32 v142, v142
	s_waitcnt vmcnt(0)
	v_fmamk_f32 v132, v132, 0x3a800000, v188
	v_rsq_f32_e32 v132, v132
	v_mul_f32_e32 v142, v0, v142
	v_mul_f32_e32 v144, v30, v142
	v_mul_f32_e32 v145, v31, v142
	v_mul_f32_e32 v146, v32, v142
	v_mul_f32_e32 v147, v33, v142
	v_cvt_pk_bf16_f32 v144, v144, v145
	v_cvt_pk_bf16_f32 v145, v146, v147
	v_mul_f32_e32 v146, v26, v142
	v_mul_f32_e32 v147, v27, v142
	v_mul_f32_e32 v148, v28, v142
	v_mul_f32_e32 v149, v29, v142
	v_cvt_pk_bf16_f32 v146, v146, v147
	v_cvt_pk_bf16_f32 v147, v148, v149
	v_add_u32_e32 v148, 0x3000, v141
	ds_write2_b64 v148, v[144:145], v[146:147] offset0:192 offset1:196
	v_mul_f32_e32 v144, v22, v142
	v_mul_f32_e32 v145, v23, v142
	v_mul_f32_e32 v146, v24, v142
	v_mul_f32_e32 v147, v25, v142
	v_cvt_pk_bf16_f32 v144, v144, v145
	v_cvt_pk_bf16_f32 v145, v146, v147
	v_mul_f32_e32 v146, v18, v142
	v_mul_f32_e32 v147, v19, v142
	v_mul_f32_e32 v143, v21, v142
	v_mul_f32_e32 v142, v20, v142
	v_mul_f32_e32 v0, v0, v132
	v_cvt_pk_bf16_f32 v146, v146, v147
	v_cvt_pk_bf16_f32 v147, v142, v143
	v_mul_f32_e32 v132, v14, v0
	v_mul_f32_e32 v133, v15, v0
	v_mul_f32_e32 v142, v16, v0
	v_mul_f32_e32 v143, v17, v0
	ds_write2_b64 v148, v[144:145], v[146:147] offset0:200 offset1:204
	v_cvt_pk_bf16_f32 v132, v132, v133
	v_cvt_pk_bf16_f32 v133, v142, v143
	v_mul_f32_e32 v142, v6, v0
	v_mul_f32_e32 v143, v7, v0
	v_mul_f32_e32 v144, v8, v0
	v_mul_f32_e32 v145, v9, v0
	v_cvt_pk_bf16_f32 v142, v142, v143
	v_cvt_pk_bf16_f32 v143, v144, v145
	v_add_u32_e32 v141, 0x3800, v141
	ds_write2_b64 v141, v[132:133], v[142:143] offset0:224 offset1:228
	v_mul_f32_e32 v132, v2, v0
	v_mul_f32_e32 v133, v3, v0
	v_mul_f32_e32 v142, v4, v0
	v_mul_f32_e32 v143, v5, v0
	v_cvt_pk_bf16_f32 v132, v132, v133
	v_cvt_pk_bf16_f32 v133, v142, v143
	v_mul_f32_e32 v142, v10, v0
	v_mul_f32_e32 v143, v11, v0
	v_mul_f32_e32 v144, v12, v0
	v_mul_f32_e32 v145, v13, v0
	v_cvt_pk_bf16_f32 v142, v142, v143
	v_cvt_pk_bf16_f32 v143, v144, v145
	ds_write2_b64 v141, v[132:133], v[142:143] offset0:232 offset1:236
	v_mov_b64_e32 v[132:133], s[62:63]
	v_mad_i64_i32 v[132:133], s[4:5], v139, s8, v[132:133]
	v_lshl_add_u64 v[132:133], s[2:3], 1, v[132:133]
	v_lshlrev_b32_e32 v0, 7, v131
	v_lshrrev_b32_e32 v148, 3, v140
	v_lshl_add_u64 v[132:133], v[132:133], 0, v[0:1]
	v_and_b32_e32 v0, 0x70, v136
	v_mul_u32_u24_e32 v140, 0x90, v148
	v_add3_u32 v149, v135, v0, v140
	ds_read_b128 v[206:209], v149
	ds_read_b128 v[210:213], v149 offset:1152
	ds_read_b128 v[214:217], v149 offset:2304
	ds_read_b128 v[218:221], v149 offset:3456
	ds_read_b128 v[222:225], v149 offset:4608
	ds_read_b128 v[228:231], v149 offset:5760
	ds_read_b128 v[232:235], v149 offset:6912
	ds_read_b128 v[236:239], v149 offset:8064
	v_lshl_add_u64 v[132:133], v[132:133], 0, v[0:1]
	v_mul_u32_u24_e32 v0, 0xd00, v148
	v_lshlrev_b32_e32 v0, 1, v0
	v_lshl_add_u64 v[144:145], v[132:133], 0, v[0:1]
	s_cmp_eq_u32 s40, 2
	s_cbranch_scc1 .Lepi_hi_skip
	s_waitcnt lgkmcnt(7)
	global_store_dwordx4 v[144:145], v[206:209], off
	s_mov_b32 s2, 0xd000
	v_add_co_u32_e32 v146, vcc, s2, v144
	s_mov_b32 s2, 0x1a000
	s_nop 0
	v_addc_co_u32_e32 v147, vcc, 0, v145, vcc
	s_waitcnt lgkmcnt(6)
	global_store_dwordx4 v[146:147], v[210:213], off
	v_add_co_u32_e32 v146, vcc, s2, v144
	s_mov_b32 s2, 0x27000
	s_nop 0
	v_addc_co_u32_e32 v147, vcc, 0, v145, vcc
	s_waitcnt lgkmcnt(5)
	global_store_dwordx4 v[146:147], v[214:217], off
	v_add_co_u32_e32 v144, vcc, s2, v144
	s_movk_i32 s2, 0xd00
	s_nop 0
	v_addc_co_u32_e32 v145, vcc, 0, v145, vcc
	s_waitcnt lgkmcnt(4)
	global_store_dwordx4 v[144:145], v[218:221], off
	v_add_u32_e32 v144, 0x34000, v0
	v_mov_b32_e32 v145, v1
	v_lshl_add_u64 v[144:145], v[132:133], 0, v[144:145]
	s_waitcnt lgkmcnt(3)
	global_store_dwordx4 v[144:145], v[222:225], off
	v_add_u32_e32 v144, 0x41000, v0
	v_mov_b32_e32 v145, v1
	v_lshl_add_u64 v[144:145], v[132:133], 0, v[144:145]
	s_waitcnt lgkmcnt(2)
	global_store_dwordx4 v[144:145], v[228:231], off
	v_add_u32_e32 v144, 0x4e000, v0
	v_mov_b32_e32 v145, v1
	v_lshl_add_u64 v[144:145], v[132:133], 0, v[144:145]
	s_waitcnt lgkmcnt(1)
	global_store_dwordx4 v[144:145], v[232:235], off
	v_add_u32_e32 v144, 0x5b000, v0
	v_mov_b32_e32 v145, v1
	v_lshl_add_u64 v[144:145], v[132:133], 0, v[144:145]
	s_waitcnt lgkmcnt(0)
	global_store_dwordx4 v[144:145], v[236:239], off
	s_cmp_eq_u32 s40, 1
	s_cbranch_scc1 .Lgx_halfdone
	s_branch .Lepi_t8

; template <int EPI>
; DI void gemm_tile(const Params& p, int layer, int mt, int nt, u16* sm, int wv) {
;     ...
; #pragma unroll
;       for (int t = 0; t < 16; ++t) {
;         const int c = lane + 64 * t, row = c >> 3, kc = c & 7;
;         const u32x4 v = *(const u32x4*)(stg + row * LSTR + kc * 8);
;         *(u32x4*)(gdst + (size_t)row * DIN + kc * 8) = v;
;       }
.Lepi_t8:
	ds_read_b128 v[206:209], v149 offset:9216
	ds_read_b128 v[210:213], v149 offset:10368
	ds_read_b128 v[214:217], v149 offset:11520
	ds_read_b128 v[218:221], v149 offset:12672
	ds_read_b128 v[222:225], v149 offset:13824
	ds_read_b128 v[228:231], v149 offset:14976
	ds_read_b128 v[232:235], v149 offset:16128
	v_add_u32_e32 v144, 0x68000, v0
	v_mov_b32_e32 v145, v1
	v_lshl_add_u64 v[144:145], v[132:133], 0, v[144:145]
	s_waitcnt lgkmcnt(6)
	global_store_dwordx4 v[144:145], v[206:209], off
	v_add_u32_e32 v144, 0x75000, v0
	v_mov_b32_e32 v145, v1
	v_lshl_add_u64 v[144:145], v[132:133], 0, v[144:145]
	s_waitcnt lgkmcnt(5)
	global_store_dwordx4 v[144:145], v[210:213], off
	v_add_u32_e32 v144, 0x82000, v0
	v_mov_b32_e32 v145, v1
	v_lshl_add_u64 v[144:145], v[132:133], 0, v[144:145]
	s_waitcnt lgkmcnt(4)
	global_store_dwordx4 v[144:145], v[214:217], off
	v_add_u32_e32 v144, 0x8f000, v0
	v_mov_b32_e32 v145, v1
	v_lshl_add_u64 v[144:145], v[132:133], 0, v[144:145]
	s_waitcnt lgkmcnt(3)
	global_store_dwordx4 v[144:145], v[218:221], off
	v_add_u32_e32 v144, 0x9c000, v0
	v_mov_b32_e32 v145, v1
	v_lshl_add_u64 v[144:145], v[132:133], 0, v[144:145]
	s_waitcnt lgkmcnt(2)
	global_store_dwordx4 v[144:145], v[222:225], off
	v_add_u32_e32 v144, 0xa9000, v0
	v_mov_b32_e32 v145, v1
	v_lshl_add_u64 v[144:145], v[132:133], 0, v[144:145]
	v_add_u32_e32 v0, 0xb6000, v0
	s_waitcnt lgkmcnt(1)
	global_store_dwordx4 v[144:145], v[228:231], off
	v_lshl_add_u64 v[144:145], v[132:133], 0, v[0:1]
	v_mad_u32_u24 v0, v148, s2, v193
	s_waitcnt lgkmcnt(0)
	global_store_dwordx4 v[144:145], v[232:235], off
	s_nop 1
	v_add_u32_e32 v140, 0x4380, v149

; DI float ex2(float x) { return __builtin_amdgcn_exp2f(x); }
; DI float lg2(float x) { return __builtin_amdgcn_logf(x); }
; DI f32x16 mfma(bf16x8 a, bf16x8 b, f32x16 c) { return __builtin_amdgcn_mfma_f32_32x32x16_bf16(a, b, c, 0, 0, 0); }
; DI void stick_pv(f32x16& s0, f32x16& s1, float& R, f32x16& o0, f32x16& o1, const u16* Vs, int dl,
;                  bool need_mask, int r, int h) {
;   float x[32];
; #pragma unroll
;   for (int t = 0; t < 2; ++t)
; #pragma unroll
;     for (int i = 0; i < 16; ++i) {
;       const int ci = 32 * t + (i & 3) + 8 * (i >> 2);
;       float a = t ? s1[i] : s0[i];
;       float z = __builtin_amdgcn_fmed3f(a, -126.f, 126.f);
;       float e = ex2(-z);
;       float lb = -lg2(1.f + e);
;       float xi = lb - z;
;       if (need_mask) {
;         bool valid = (ci < dl);
;         xi = valid ? xi : 0.f;
;         lb = valid ? lb : -INFINITY;
;       }
;       x[16 * t + i] = xi;
;       if (t) s1[i] = lb; else s0[i] = lb;
;     }
; template <int MODE>
; DI void attn_item(const Params& p, int layer, int b, int head, int qblk, u16* sm, volatile LAS int* s_done_, int wv) {
;     ...
;               f32x16 sa[2];
; #pragma unroll
;               for (int e = 0; e < 16; ++e) { sa[0][e] = 0.f; sa[1][e] = 0.f; }
; #pragma unroll
;               for (int t = 0; t < 2; ++t)
; #pragma unroll
;                 for (int ks = 0; ks < 4; ++ks) {
;                   bf16x8 kf = ldsv(Kc + (32 * t + r) * LSTR + ks * 16 + 8 * h);
;                   sa[t] = mfma(kf, qf[ks], sa[t]);
;                 }
;               stick_pv(sa[0], sa[1], R, o[0], o[1], Vc, dl, need_mask, r, h);
.LBB0_224:
	s_or_b64 exec, exec, s[6:7]
	s_waitcnt lgkmcnt(0)
	s_barrier
	s_and_saveexec_b64 s[6:7], s[2:3]
	s_cbranch_execz .LBB0_210
	v_cmp_lt_i32_e64 s[2:3], v164, v176
	v_cmp_eq_u32_e64 s[44:45], 0, v64
	s_and_b64 s[2:3], s[2:3], s[44:45]
	s_and_saveexec_b64 s[18:19], s[2:3]
	s_cbranch_execz .LBB0_234
	v_add_u32_e32 v0, 63, v164
	v_cmp_lt_i32_e64 s[44:45], v0, v148
	v_add_u32_e32 v0, v152, v181
	s_waitcnt vmcnt(3)
	s_waitcnt vmcnt(2)
	ds_read_b128 v[48:51], v0
	ds_read_b128 v[52:55], v0 offset:32
	ds_read_b128 v[240:243], v0 offset:64
	ds_read_b128 v[244:247], v0 offset:96
	ds_read_b128 v[204:207], v0 offset:4640
	v_cmp_lt_i32_e64 s[2:3], 0, v183
	s_waitcnt lgkmcnt(4)
	v_mfma_f32_32x32x16_bf16 v[64:79], v[48:51], v[88:91], 0
	s_or_b64 s[2:3], s[44:45], s[2:3]
	v_add_f32_e32 v236, 0, v184
	s_waitcnt lgkmcnt(3)
	v_mfma_f32_32x32x16_bf16 v[64:79], v[52:55], v[80:83], v[64:79]
	s_waitcnt lgkmcnt(2)
	v_mfma_f32_32x32x16_bf16 v[64:79], v[240:243], v[84:87], v[64:79]
	ds_read_b128 v[240:243], v0 offset:4608
	s_waitcnt lgkmcnt(2)
	v_mfma_f32_32x32x16_bf16 v[64:79], v[244:247], v[92:95], v[64:79]
	ds_read_b128 v[244:247], v0 offset:4672
	s_waitcnt vmcnt(0) lgkmcnt(1)
	v_mfma_f32_32x32x16_bf16 v[48:63], v[240:243], v[88:91], 0
	ds_read_b128 v[240:243], v0 offset:4704
	v_mfma_f32_32x32x16_bf16 v[48:63], v[204:207], v[80:83], v[48:63]
	s_waitcnt lgkmcnt(1)
	v_mfma_f32_32x32x16_bf16 v[48:63], v[244:247], v[84:87], v[48:63]
	s_nop 3
	v_med3_f32 v0, v64, s94, v198
	v_exp_f32_e64 v14, -v0
	s_nop 0
	v_add_f32_e32 v14, 1.0, v14
	v_log_f32_e32 v15, v14
	s_waitcnt lgkmcnt(0)
	v_mfma_f32_32x32x16_bf16 v[48:63], v[240:243], v[92:95], v[48:63]
	v_sub_f32_e64 v0, -v15, v0
	v_cndmask_b32_e64 v14, 0, v0, s[2:3]
	v_med3_f32 v0, v65, s94, v198
	v_cndmask_b32_e64 v165, v199, -v15, s[2:3]
	v_exp_f32_e64 v15, -v0
	v_cmp_lt_i32_e64 s[2:3], 1, v183
	s_or_b64 s[2:3], s[44:45], s[2:3]
	v_add_f32_e32 v15, 1.0, v15
	v_log_f32_e32 v15, v15
	s_nop 0
	v_sub_f32_e64 v0, -v15, v0
	v_cndmask_b32_e64 v64, 0, v0, s[2:3]
	v_med3_f32 v0, v66, s94, v198
	v_cndmask_b32_e64 v185, v199, -v15, s[2:3]
	v_exp_f32_e64 v15, -v0
	v_cmp_lt_i32_e64 s[2:3], 2, v183
	s_or_b64 s[2:3], s[44:45], s[2:3]
	v_add_f32_e32 v15, 1.0, v15
	v_log_f32_e32 v15, v15
	s_nop 0
	v_sub_f32_e64 v0, -v15, v0
	v_cndmask_b32_e64 v66, 0, v0, s[2:3]
	v_med3_f32 v0, v67, s94, v198
	v_cndmask_b32_e64 v186, v199, -v15, s[2:3]
	v_exp_f32_e64 v15, -v0
	v_cmp_lt_i32_e64 s[2:3], 3, v183
	s_or_b64 s[2:3], s[44:45], s[2:3]
	v_add_f32_e32 v15, 1.0, v15
	v_log_f32_e32 v15, v15
	s_nop 0
	v_sub_f32_e64 v0, -v15, v0
	v_cndmask_b32_e64 v166, 0, v0, s[2:3]
	v_med3_f32 v0, v68, s94, v198
	v_cndmask_b32_e64 v204, v199, -v15, s[2:3]
	v_exp_f32_e64 v15, -v0
	v_cmp_lt_i32_e64 s[2:3], 8, v183
	s_or_b64 s[2:3], s[44:45], s[2:3]
	v_add_f32_e32 v15, 1.0, v15
	v_log_f32_e32 v15, v15
	s_nop 0
	v_sub_f32_e64 v0, -v15, v0
	v_cndmask_b32_e64 v205, v199, -v15, s[2:3]
	v_med3_f32 v15, v69, s94, v198
	v_exp_f32_e64 v65, -v15
	v_cndmask_b32_e64 v0, 0, v0, s[2:3]
	v_cmp_lt_i32_e64 s[2:3], 9, v183
	s_or_b64 s[2:3], s[44:45], s[2:3]
	v_add_f32_e32 v65, 1.0, v65
	v_log_f32_e32 v65, v65
	s_nop 0
	v_sub_f32_e64 v15, -v65, v15
	v_cndmask_b32_e64 v207, 0, v15, s[2:3]
	v_med3_f32 v15, v70, s94, v198
	v_cndmask_b32_e64 v206, v199, -v65, s[2:3]
	v_exp_f32_e64 v65, -v15
	v_cmp_lt_i32_e64 s[2:3], 10, v183
	s_or_b64 s[2:3], s[44:45], s[2:3]
	v_add_f32_e32 v0, v0, v207
	v_add_f32_e32 v65, 1.0, v65
	v_log_f32_e32 v65, v65
	s_nop 0
	v_sub_f32_e64 v15, -v65, v15
	v_cndmask_b32_e64 v209, 0, v15, s[2:3]
	v_med3_f32 v15, v71, s94, v198
	v_cndmask_b32_e64 v208, v199, -v65, s[2:3]
	v_exp_f32_e64 v65, -v15
	v_cmp_lt_i32_e64 s[2:3], 11, v183
	s_or_b64 s[2:3], s[44:45], s[2:3]
	v_add_f32_e32 v65, 1.0, v65
	v_log_f32_e32 v65, v65
	s_nop 0
	v_sub_f32_e64 v15, -v65, v15
	v_cndmask_b32_e64 v211, 0, v15, s[2:3]
	v_med3_f32 v15, v72, s94, v198
	v_cndmask_b32_e64 v210, v199, -v65, s[2:3]
	v_exp_f32_e64 v65, -v15
	v_cmp_lt_i32_e64 s[2:3], 16, v183
	s_or_b64 s[2:3], s[44:45], s[2:3]
	v_add_f32_e32 v65, 1.0, v65
	v_log_f32_e32 v65, v65
	s_nop 0
	v_sub_f32_e64 v15, -v65, v15
	v_cndmask_b32_e64 v67, 0, v15, s[2:3]
	v_med3_f32 v15, v73, s94, v198
	v_cndmask_b32_e64 v212, v199, -v65, s[2:3]
	v_exp_f32_e64 v65, -v15
	v_cmp_lt_i32_e64 s[2:3], 17, v183
	s_or_b64 s[2:3], s[44:45], s[2:3]
	v_add_f32_e32 v65, 1.0, v65
	v_log_f32_e32 v65, v65
	s_nop 0
	v_sub_f32_e64 v15, -v65, v15
	v_cndmask_b32_e64 v214, 0, v15, s[2:3]
	v_med3_f32 v15, v74, s94, v198
	v_cndmask_b32_e64 v213, v199, -v65, s[2:3]
	v_exp_f32_e64 v65, -v15
	v_cmp_lt_i32_e64 s[2:3], 18, v183
	s_or_b64 s[2:3], s[44:45], s[2:3]
	v_add_f32_e32 v65, 1.0, v65
	v_log_f32_e32 v65, v65
	s_nop 0
	v_sub_f32_e64 v15, -v65, v15
	v_cndmask_b32_e64 v216, 0, v15, s[2:3]
	v_med3_f32 v15, v75, s94, v198
	v_cndmask_b32_e64 v215, v199, -v65, s[2:3]
	v_exp_f32_e64 v65, -v15
	v_cmp_lt_i32_e64 s[2:3], 19, v183
	s_or_b64 s[2:3], s[44:45], s[2:3]
	v_add_f32_e32 v65, 1.0, v65
	v_log_f32_e32 v65, v65
	s_nop 0
	v_sub_f32_e64 v15, -v65, v15
	v_cndmask_b32_e64 v218, 0, v15, s[2:3]
	v_med3_f32 v15, v76, s94, v198
	v_cndmask_b32_e64 v217, v199, -v65, s[2:3]
	v_exp_f32_e64 v65, -v15
	v_cmp_lt_i32_e64 s[2:3], 24, v183
	s_or_b64 s[2:3], s[44:45], s[2:3]
	v_add_f32_e32 v65, 1.0, v65
	v_log_f32_e32 v65, v65
	s_nop 0
	v_sub_f32_e64 v15, -v65, v15
	v_cndmask_b32_e64 v70, 0, v15, s[2:3]
	v_med3_f32 v15, v77, s94, v198
	v_cndmask_b32_e64 v76, v199, -v65, s[2:3]
	v_exp_f32_e64 v65, -v15
	v_cmp_lt_i32_e64 s[2:3], 25, v183
	s_or_b64 s[2:3], s[44:45], s[2:3]
	v_add_f32_e32 v65, 1.0, v65
	v_log_f32_e32 v65, v65
	s_nop 0
	v_sub_f32_e64 v15, -v65, v15
	v_cndmask_b32_e64 v68, 0, v15, s[2:3]
; DI float ex2(float x) { return __builtin_amdgcn_exp2f(x); }
; DI float lg2(float x) { return __builtin_amdgcn_logf(x); }
; DI void stick_pv(f32x16& s0, f32x16& s1, float& R, f32x16& o0, f32x16& o1, const u16* Vs, int dl,
;                  bool need_mask, int r, int h) {
;     ...
;     for (int i = 0; i < 16; ++i) {
;       const int ci = 32 * t + (i & 3) + 8 * (i >> 2);
;       float a = t ? s1[i] : s0[i];
;       float z = __builtin_amdgcn_fmed3f(a, -126.f, 126.f);
;       float e = ex2(-z);
;       float lb = -lg2(1.f + e);
;       float xi = lb - z;
;       if (need_mask) {
;         bool valid = (ci < dl);
;         xi = valid ? xi : 0.f;
;         lb = valid ? lb : -INFINITY;
;       }
;       x[16 * t + i] = xi;
;       if (t) s1[i] = lb; else s0[i] = lb;
;     }
;   float gs[8], pg[8], pr[8];
; #pragma unroll
;   for (int g = 0; g < 8; ++g) {
;     gs[g] = (x[4 * g] + x[4 * g + 1]) + (x[4 * g + 2] + x[4 * g + 3]);
;     pg[g] = shx(gs[g], r + 32 * h);
;     pr[g] = gs[g] + pg[g];
	v_med3_f32 v15, v78, s94, v198
	v_cndmask_b32_e64 v77, v199, -v65, s[2:3]
	v_exp_f32_e64 v65, -v15
	v_cmp_lt_i32_e64 s[2:3], 26, v183
	s_or_b64 s[2:3], s[44:45], s[2:3]
	v_add_f32_e32 v65, 1.0, v65
	v_log_f32_e32 v65, v65
	s_nop 0
	v_sub_f32_e64 v15, -v65, v15
	v_cndmask_b32_e64 v72, 0, v15, s[2:3]
	v_med3_f32 v15, v79, s94, v198
	v_cndmask_b32_e64 v78, v199, -v65, s[2:3]
	v_exp_f32_e64 v65, -v15
	v_cmp_lt_i32_e64 s[2:3], 27, v183
	s_or_b64 s[2:3], s[44:45], s[2:3]
	v_add_f32_e32 v65, 1.0, v65
	v_log_f32_e32 v65, v65
	s_nop 0
	v_sub_f32_e64 v15, -v65, v15
	v_cndmask_b32_e64 v74, 0, v15, s[2:3]
	v_med3_f32 v15, v48, s94, v198
	v_exp_f32_e64 v48, -v15
	v_cndmask_b32_e64 v79, v199, -v65, s[2:3]
	v_cmp_lt_i32_e64 s[2:3], 32, v183
	s_or_b64 s[2:3], s[44:45], s[2:3]
	v_add_f32_e32 v48, 1.0, v48
	v_log_f32_e32 v48, v48
	s_nop 0
	v_sub_f32_e64 v15, -v48, v15
	v_cndmask_b32_e64 v69, 0, v15, s[2:3]
	v_med3_f32 v15, v49, s94, v198
	v_cndmask_b32_e64 v167, v199, -v48, s[2:3]
	v_exp_f32_e64 v48, -v15
	v_cmp_lt_i32_e64 s[2:3], 33, v183
	s_or_b64 s[2:3], s[44:45], s[2:3]
	v_add_f32_e32 v48, 1.0, v48
	v_log_f32_e32 v48, v48
	s_nop 0
	v_sub_f32_e64 v15, -v48, v15
	v_cndmask_b32_e64 v220, 0, v15, s[2:3]
	v_med3_f32 v15, v50, s94, v198
	v_cndmask_b32_e64 v219, v199, -v48, s[2:3]
	v_exp_f32_e64 v48, -v15
	v_cmp_lt_i32_e64 s[2:3], 34, v183
	s_or_b64 s[2:3], s[44:45], s[2:3]
	v_add_f32_e32 v48, 1.0, v48
	v_log_f32_e32 v48, v48
	s_nop 0
	v_sub_f32_e64 v15, -v48, v15
	v_cndmask_b32_e64 v222, 0, v15, s[2:3]
	v_med3_f32 v15, v51, s94, v198
	v_cndmask_b32_e64 v221, v199, -v48, s[2:3]
	v_exp_f32_e64 v48, -v15
	v_cmp_lt_i32_e64 s[2:3], 35, v183
	s_or_b64 s[2:3], s[44:45], s[2:3]
	v_add_f32_e32 v48, 1.0, v48
	v_log_f32_e32 v48, v48
	s_nop 0
	v_sub_f32_e64 v15, -v48, v15
	v_cndmask_b32_e64 v224, 0, v15, s[2:3]
	v_med3_f32 v15, v52, s94, v198
	v_cndmask_b32_e64 v223, v199, -v48, s[2:3]
	v_exp_f32_e64 v48, -v15
	v_cmp_lt_i32_e64 s[2:3], 40, v183
	s_or_b64 s[2:3], s[44:45], s[2:3]
	v_add_f32_e32 v48, 1.0, v48
	v_log_f32_e32 v48, v48
	s_nop 0
	v_sub_f32_e64 v15, -v48, v15
	v_cndmask_b32_e64 v49, 0, v15, s[2:3]
	v_med3_f32 v15, v53, s94, v198
	v_cndmask_b32_e64 v52, v199, -v48, s[2:3]
	v_exp_f32_e64 v48, -v15
	v_cmp_lt_i32_e64 s[2:3], 41, v183
	s_or_b64 s[2:3], s[44:45], s[2:3]
	v_add_f32_e32 v48, 1.0, v48
	v_log_f32_e32 v48, v48
	s_nop 0
	v_sub_f32_e64 v15, -v48, v15
	v_cndmask_b32_e64 v53, 0, v15, s[2:3]
	v_med3_f32 v15, v54, s94, v198
	v_cndmask_b32_e64 v75, v199, -v48, s[2:3]
	v_exp_f32_e64 v48, -v15
	v_cmp_lt_i32_e64 s[2:3], 42, v183
	s_or_b64 s[2:3], s[44:45], s[2:3]
	v_add_f32_e32 v48, 1.0, v48
	v_log_f32_e32 v48, v48
	s_nop 0
	v_sub_f32_e64 v15, -v48, v15
	v_cndmask_b32_e64 v225, 0, v15, s[2:3]
	v_med3_f32 v15, v55, s94, v198
	v_cndmask_b32_e64 v226, v199, -v48, s[2:3]
	v_exp_f32_e64 v48, -v15
	v_cmp_lt_i32_e64 s[2:3], 43, v183
	s_or_b64 s[2:3], s[44:45], s[2:3]
	v_add_f32_e32 v48, 1.0, v48
	v_log_f32_e32 v48, v48
	s_nop 0
	v_sub_f32_e64 v15, -v48, v15
	v_cndmask_b32_e64 v227, 0, v15, s[2:3]
	v_med3_f32 v15, v56, s94, v198
	v_cndmask_b32_e64 v228, v199, -v48, s[2:3]
	v_exp_f32_e64 v48, -v15
	v_cmp_lt_i32_e64 s[2:3], 48, v183
	s_or_b64 s[2:3], s[44:45], s[2:3]
	v_add_f32_e32 v48, 1.0, v48
	v_log_f32_e32 v50, v48
	s_nop 0
	v_sub_f32_e64 v15, -v50, v15
	v_cndmask_b32_e64 v48, 0, v15, s[2:3]
	v_med3_f32 v15, v57, s94, v198
	v_cndmask_b32_e64 v56, v199, -v50, s[2:3]
	v_exp_f32_e64 v50, -v15
	v_cmp_lt_i32_e64 s[2:3], 49, v183
	s_or_b64 s[2:3], s[44:45], s[2:3]
	v_add_f32_e32 v50, 1.0, v50
	v_log_f32_e32 v51, v50
	s_nop 0
	v_sub_f32_e64 v15, -v51, v15
	v_cndmask_b32_e64 v50, 0, v15, s[2:3]
	v_med3_f32 v15, v58, s94, v198
	v_cndmask_b32_e64 v57, v199, -v51, s[2:3]
	v_exp_f32_e64 v51, -v15
	v_cmp_lt_i32_e64 s[2:3], 50, v183
	s_or_b64 s[2:3], s[44:45], s[2:3]
	v_add_f32_e32 v51, 1.0, v51
	v_log_f32_e32 v51, v51
	s_nop 0
	v_sub_f32_e64 v15, -v51, v15
	v_cndmask_b32_e64 v58, 0, v15, s[2:3]
	v_med3_f32 v15, v59, s94, v198
	v_cndmask_b32_e64 v229, v199, -v51, s[2:3]
	v_exp_f32_e64 v51, -v15
	v_cmp_lt_i32_e64 s[2:3], 51, v183
	s_or_b64 s[2:3], s[44:45], s[2:3]
	v_add_f32_e32 v51, 1.0, v51
	v_log_f32_e32 v51, v51
	s_nop 0
	v_sub_f32_e64 v15, -v51, v15
	v_cndmask_b32_e64 v59, 0, v15, s[2:3]
	v_med3_f32 v15, v60, s94, v198
	v_cndmask_b32_e64 v230, v199, -v51, s[2:3]
	v_exp_f32_e64 v51, -v15
	v_cmp_lt_i32_e64 s[2:3], 56, v183
	s_or_b64 s[2:3], s[44:45], s[2:3]
	v_add_f32_e32 v54, v58, v59
	v_add_f32_e32 v51, 1.0, v51
	v_log_f32_e32 v51, v51
	s_nop 0
	v_sub_f32_e64 v15, -v51, v15
	v_cndmask_b32_e64 v55, 0, v15, s[2:3]
	v_med3_f32 v15, v61, s94, v198
	v_cndmask_b32_e64 v60, v199, -v51, s[2:3]
	v_exp_f32_e64 v51, -v15
	v_cmp_lt_i32_e64 s[2:3], 57, v183
	s_or_b64 s[2:3], s[44:45], s[2:3]
	v_add_f32_e32 v51, 1.0, v51
	v_log_f32_e32 v51, v51
	s_nop 0
	v_sub_f32_e64 v15, -v51, v15
	v_cndmask_b32_e64 v61, 0, v15, s[2:3]
	v_med3_f32 v15, v62, s94, v198
	v_cndmask_b32_e64 v231, v199, -v51, s[2:3]
	v_exp_f32_e64 v51, -v15
	v_cmp_lt_i32_e64 s[2:3], 58, v183
	s_or_b64 s[2:3], s[44:45], s[2:3]
	v_add_f32_e32 v51, 1.0, v51
	v_log_f32_e32 v51, v51
	s_nop 0
	v_sub_f32_e64 v15, -v51, v15
	v_cndmask_b32_e64 v62, 0, v15, s[2:3]
	v_med3_f32 v15, v63, s94, v198
	v_cndmask_b32_e64 v232, v199, -v51, s[2:3]
	v_exp_f32_e64 v51, -v15
	v_cmp_lt_i32_e64 s[2:3], 59, v183
	s_or_b64 s[2:3], s[44:45], s[2:3]
	v_add_f32_e32 v51, 1.0, v51
	v_log_f32_e32 v51, v51
	s_nop 0
	v_sub_f32_e64 v15, -v51, v15
	v_cndmask_b32_e64 v63, 0, v15, s[2:3]
	v_add_f32_e32 v15, v209, v211
	v_cndmask_b32_e64 v233, v199, -v51, s[2:3]
	v_add_f32_e32 v15, v0, v15
	v_add_f32_e32 v0, v67, v214
	v_add_f32_e32 v51, v216, v218
	v_add_f32_e32 v0, v0, v51
	ds_bpermute_b32 v234, v180, v0
	v_add_f32_e32 v51, v222, v224
	ds_bpermute_b32 v65, v180, v15
	s_mov_b32 s2, 0xc3200000
	s_waitcnt lgkmcnt(1)
; DI float ex2(float x) { return __builtin_amdgcn_exp2f(x); }
; DI f32x16 mfma(bf16x8 a, bf16x8 b, f32x16 c) { return __builtin_amdgcn_mfma_f32_32x32x16_bf16(a, b, c, 0, 0, 0); }
; DI void stick_pv(f32x16& s0, f32x16& s1, float& R, f32x16& o0, f32x16& o1, const u16* Vs, int dl,
;                  bool need_mask, int r, int h) {
;     ...
;   float gs[8], pg[8], pr[8];
; #pragma unroll
;   for (int g = 0; g < 8; ++g) {
;     gs[g] = (x[4 * g] + x[4 * g + 1]) + (x[4 * g + 2] + x[4 * g + 3]);
;     pg[g] = shx(gs[g], r + 32 * h);
;     pr[g] = gs[g] + pg[g];
;   }
;   float suf = 0.f;
; #pragma unroll
;   for (int g = 7; g >= 0; --g) {
;     float base = R + suf + (h == 0 ? pg[g] : 0.f);
;     float t3 = base, t2 = t3 + x[4 * g + 3], t1 = t2 + x[4 * g + 2], t0 = t1 + x[4 * g + 1];
;     const int i = 4 * (g & 3);
;     if (g >= 4) {
;       s1[i] = ex2(s1[i] + t0); s1[i + 1] = ex2(s1[i + 1] + t1); s1[i + 2] = ex2(s1[i + 2] + t2); s1[i + 3] = ex2(s1[i + 3] + t3);
;     } else {
;       s0[i] = ex2(s0[i] + t0); s0[i + 1] = ex2(s0[i + 1] + t1); s0[i + 2] = ex2(s0[i + 2] + t2); s0[i + 3] = ex2(s0[i + 3] + t3);
;     }
;     suf += pr[g];
;   }
;   R += suf;
; #pragma unroll
;   for (int kk = 0; kk < 4; ++kk) {
;     const int s = kk & 1;
;     unsigned u0, u1, u2, u3;
;     if (kk < 2) {
;       u0 = pk2(s0[8 * s], s0[8 * s + 1]); u1 = pk2(s0[8 * s + 2], s0[8 * s + 3]);
;       u2 = pk2(s0[8 * s + 4], s0[8 * s + 5]); u3 = pk2(s0[8 * s + 6], s0[8 * s + 7]);
;     } else {
;       u0 = pk2(s1[8 * s], s1[8 * s + 1]); u1 = pk2(s1[8 * s + 2], s1[8 * s + 3]);
;       u2 = pk2(s1[8 * s + 4], s1[8 * s + 5]); u3 = pk2(s1[8 * s + 6], s1[8 * s + 7]);
;     }
;     u32x4 uu = {u0, u1, u2, u3};
;     bf16x8 pf = __builtin_bit_cast(bf16x8, uu);
;     bf16x8 v0 = ldsv(Vs + r * LSTR + kk * 16 + 8 * h);
;     bf16x8 v1 = ldsv(Vs + (32 + r) * LSTR + kk * 16 + 8 * h);
;     o0 = mfma(v0, pf, o0);
;     o1 = mfma(v1, pf, o1);
;   }
; template <int MODE>
; DI void attn_item(const Params& p, int layer, int b, int head, int qblk, u16* sm, volatile LAS int* s_done_, int wv) {
;     ...
;               wdone = __all(R < -160.f) ? 1 : 0;
	v_add_f32_e32 v67, v0, v234
	v_add_f32_e32 v0, v69, v220
	v_add_f32_e32 v71, v0, v51
	v_add_f32_e32 v0, v49, v53
	v_add_f32_e32 v49, v225, v227
	v_add_f32_e32 v0, v0, v49
	v_add_f32_e32 v49, v55, v61
	v_add_f32_e32 v51, v62, v63
	v_add_f32_e32 v48, v48, v50
	v_add_f32_e32 v49, v49, v51
	ds_bpermute_b32 v55, v180, v49
	ds_bpermute_b32 v235, v180, v0
	ds_bpermute_b32 v69, v180, v71
	s_waitcnt lgkmcnt(3)
	v_add_f32_e32 v14, v14, v64
	v_add_f32_e32 v15, v15, v65
	s_waitcnt lgkmcnt(2)
	v_add_f32_e32 v48, v48, v54
	v_add_f32_e32 v49, v49, v55
	s_waitcnt lgkmcnt(1)
	v_add_f32_e32 v73, v0, v235
	ds_bpermute_b32 v0, v180, v48
	v_cndmask_b32_e32 v51, 0, v55, vcc
	v_add_f32_e32 v51, v236, v51
	v_add_f32_e32 v54, v63, v51
	v_add_f32_e32 v51, v233, v51
	s_waitcnt lgkmcnt(0)
	v_add_f32_e32 v48, v48, v0
	v_add_f32_e32 v49, v49, v1
	v_exp_f32_e32 v233, v51
	v_add_f32_e32 v51, v184, v49
	v_cndmask_b32_e32 v0, 0, v0, vcc
	v_add_f32_e32 v0, v0, v51
	v_add_f32_e32 v55, v62, v54
	v_add_f32_e32 v54, v232, v54
	v_add_f32_e32 v51, v59, v0
	v_exp_f32_e32 v232, v54
	v_add_f32_e32 v54, v58, v51
	v_add_f32_e32 v50, v50, v54
	v_add_f32_e32 v50, v56, v50
	v_exp_f32_e32 v237, v50
	v_add_f32_e32 v50, v57, v54
	v_exp_f32_e32 v238, v50
	v_add_f32_e32 v50, v229, v51
	v_pk_add_f32 v[48:49], v[48:49], v[48:49] op_sel:[0,1] op_sel_hi:[1,0]
	v_exp_f32_e32 v229, v50
	v_add_f32_e32 v49, v184, v48
	v_cndmask_b32_e32 v50, 0, v235, vcc
	v_add_f32_e32 v49, v50, v49
	v_add_f32_e32 v50, v227, v49
	v_add_f32_e32 v51, v225, v50
	v_add_f32_e32 v53, v53, v51
	v_add_f32_e32 v51, v75, v51
	v_add_f32_e32 v50, v226, v50
	v_add_f32_e32 v49, v228, v49
	v_mov_b32_e32 v75, v48
	v_exp_f32_e32 v227, v51
	v_exp_f32_e32 v226, v50
	v_exp_f32_e32 v228, v49
	v_add_f32_e32 v50, v70, v68
	v_add_f32_e32 v51, v71, v69
	v_add_f32_e32 v48, v72, v74
	v_add_f32_e32 v49, v73, v75
	v_add_f32_e32 v52, v52, v53
	v_add_f32_e32 v50, v50, v48
	v_add_f32_e32 v51, v51, v49
	ds_bpermute_b32 v48, v180, v50
	v_exp_f32_e32 v225, v52
	v_cndmask_b32_e32 v52, 0, v69, vcc
	v_add_f32_e32 v49, v184, v49
	v_add_f32_e32 v49, v52, v49
	v_add_f32_e32 v52, v224, v49
	v_add_f32_e32 v49, v223, v49
	s_waitcnt lgkmcnt(0)
	v_add_f32_e32 v50, v50, v48
	v_exp_f32_e32 v73, v49
	v_add_f32_e32 v49, v184, v51
	v_cndmask_b32_e32 v48, 0, v48, vcc
	v_add_f32_e32 v53, v222, v52
	v_add_f32_e32 v48, v48, v49
	v_add_f32_e32 v54, v220, v53
	v_add_f32_e32 v52, v221, v52
	v_add_f32_e32 v49, v74, v48
	v_add_f32_e32 v54, v167, v54
	v_exp_f32_e32 v71, v52
	v_add_f32_e32 v52, v72, v49
	v_add_f32_e32 v49, v78, v49
	v_add_f32_e32 v48, v79, v48
	v_add_f32_e32 v167, v50, v51
	v_exp_f32_e32 v74, v49
	v_exp_f32_e32 v75, v48
	v_add_f32_e32 v48, v184, v167
	v_cndmask_b32_e32 v49, 0, v234, vcc
	v_add_f32_e32 v48, v49, v48
	v_add_f32_e32 v49, v218, v48
	v_add_f32_e32 v50, v216, v49
	v_add_f32_e32 v49, v215, v49
	v_add_f32_e32 v48, v217, v48
	v_exp_f32_e32 v78, v49
	v_exp_f32_e32 v79, v48
	v_add_f32_e32 v48, v66, v166
	v_add_f32_e32 v49, v67, v167
	v_add_f32_e32 v53, v219, v53
	v_add_f32_e32 v51, v214, v50
	v_add_f32_e32 v50, v213, v50
	v_add_f32_e32 v14, v14, v48
	v_add_f32_e32 v15, v15, v49
	v_exp_f32_e32 v70, v53
	v_add_f32_e32 v53, v68, v52
	v_add_f32_e32 v52, v77, v52
	v_exp_f32_e32 v77, v50
	v_cndmask_b32_e32 v50, 0, v65, vcc
	ds_bpermute_b32 v48, v180, v14
	v_add_f32_e32 v49, v184, v49
	v_add_f32_e32 v49, v50, v49
	v_add_f32_e32 v51, v212, v51
	v_add_f32_e32 v50, v211, v49
	v_add_f32_e32 v53, v76, v53
	v_exp_f32_e32 v76, v51
	v_add_f32_e32 v51, v209, v50
	v_exp_f32_e32 v72, v52
	v_add_f32_e32 v52, v207, v51
	v_add_f32_e32 v51, v206, v51
	v_exp_f32_e32 v68, v53
	s_waitcnt lgkmcnt(0)
	v_add_f32_e32 v14, v14, v48
	v_exp_f32_e32 v53, v51
	v_add_f32_e32 v51, v184, v15
	v_cndmask_b32_e32 v48, 0, v48, vcc
	v_add_f32_e32 v48, v48, v51
	v_add_f32_e32 v51, v166, v48
	v_add_f32_e32 v61, v61, v55
	v_add_f32_e32 v55, v231, v55
	v_exp_f32_e32 v69, v54
	v_add_f32_e32 v54, v66, v51
	v_exp_f32_e32 v231, v55
	v_add_f32_e32 v55, v64, v54
	v_add_f32_e32 v52, v205, v52
	v_add_f32_e32 v50, v208, v50
	v_add_f32_e32 v49, v210, v49
	v_add_f32_e32 v55, v165, v55
	v_add_f32_e32 v54, v185, v54
	v_add_f32_e32 v51, v186, v51
	v_add_f32_e32 v48, v204, v48
	v_exp_f32_e32 v52, v52
	v_exp_f32_e32 v50, v50
	v_exp_f32_e32 v49, v49
	v_exp_f32_e32 v55, v55
	v_exp_f32_e32 v54, v54
	v_exp_f32_e32 v56, v51
	v_exp_f32_e32 v48, v48
	v_add_f32_e32 v60, v60, v61
	v_exp_f32_e32 v236, v60
	v_cvt_pk_bf16_f32 v51, v50, v49
	v_cvt_pk_bf16_f32 v50, v52, v53
	v_cvt_pk_bf16_f32 v49, v56, v48
	v_cvt_pk_bf16_f32 v48, v55, v54
	ds_read_b128 v[52:55], v155 offset:13824
	ds_read_b128 v[56:59], v155 offset:9216
	ds_read_b128 v[60:63], v155 offset:9248
	s_waitcnt lgkmcnt(2)
	v_mfma_f32_32x32x16_bf16 v[16:31], v[52:55], v[48:51], v[16:31]
	ds_read_b128 v[52:55], v155 offset:13856
	v_add_f32_e32 v0, v230, v0
	v_exp_f32_e32 v0, v0
	v_add_f32_e32 v14, v14, v15
	v_add_f32_e32 v184, v184, v14
	v_cmp_gt_f32_e64 s[2:3], s2, v184
	s_cmp_eq_u64 s[2:3], exec
	s_waitcnt lgkmcnt(2)
	v_mfma_f32_32x32x16_bf16 v[32:47], v[56:59], v[48:51], v[32:47]
	v_cvt_pk_bf16_f32 v51, v74, v75
	v_cvt_pk_bf16_f32 v50, v68, v72
	v_cvt_pk_bf16_f32 v49, v78, v79
	v_cvt_pk_bf16_f32 v48, v76, v77
	s_cselect_b64 s[2:3], -1, 0
	v_cndmask_b32_e64 v64, 0, 1, s[2:3]
	s_waitcnt lgkmcnt(1)
	v_mfma_f32_32x32x16_bf16 v[32:47], v[60:63], v[48:51], v[32:47]
	s_waitcnt lgkmcnt(0)
	v_mfma_f32_32x32x16_bf16 v[16:31], v[52:55], v[48:51], v[16:31]
	ds_read_b128 v[52:55], v155 offset:9280
	ds_read_b128 v[56:59], v155 offset:13888
	v_cvt_pk_bf16_f32 v51, v226, v228
	v_cvt_pk_bf16_f32 v50, v225, v227
	v_cvt_pk_bf16_f32 v49, v71, v73
	v_cvt_pk_bf16_f32 v48, v69, v70
	s_waitcnt lgkmcnt(1)
	s_nop 0
	v_mfma_f32_32x32x16_bf16 v[32:47], v[52:55], v[48:51], v[32:47]
	s_waitcnt lgkmcnt(0)
	v_mfma_f32_32x32x16_bf16 v[16:31], v[56:59], v[48:51], v[16:31]
	ds_read_b128 v[52:55], v155 offset:9312
	ds_read_b128 v[56:59], v155 offset:13920
	v_cvt_pk_bf16_f32 v51, v232, v233
	v_cvt_pk_bf16_f32 v50, v236, v231
	v_cvt_pk_bf16_f32 v49, v229, v0
	v_cvt_pk_bf16_f32 v48, v237, v238
	s_waitcnt lgkmcnt(1)
	s_nop 0
	v_mfma_f32_32x32x16_bf16 v[32:47], v[52:55], v[48:51], v[32:47]
	s_waitcnt lgkmcnt(0)
	v_mfma_f32_32x32x16_bf16 v[16:31], v[56:59], v[48:51], v[16:31]
	s_or_b64 exec, exec, s[18:19]
	s_and_saveexec_b64 s[44:45], s[42:43]
	s_cbranch_execnz .LBB0_235

; DI float ex2(float x) { return __builtin_amdgcn_exp2f(x); }
; DI float lg2(float x) { return __builtin_amdgcn_logf(x); }
; DI f32x16 mfma(bf16x8 a, bf16x8 b, f32x16 c) { return __builtin_amdgcn_mfma_f32_32x32x16_bf16(a, b, c, 0, 0, 0); }
; DI void stick_pv(f32x16& s0, f32x16& s1, float& R, f32x16& o0, f32x16& o1, const u16* Vs, int dl,
;                  bool need_mask, int r, int h) {
;   float x[32];
; #pragma unroll
;   for (int t = 0; t < 2; ++t)
; #pragma unroll
;     for (int i = 0; i < 16; ++i) {
;       const int ci = 32 * t + (i & 3) + 8 * (i >> 2);
;       float a = t ? s1[i] : s0[i];
;       float z = __builtin_amdgcn_fmed3f(a, -126.f, 126.f);
;       float e = ex2(-z);
;       float lb = -lg2(1.f + e);
;       float xi = lb - z;
;       if (need_mask) {
;         bool valid = (ci < dl);
;         xi = valid ? xi : 0.f;
;         lb = valid ? lb : -INFINITY;
;       }
;       x[16 * t + i] = xi;
;       if (t) s1[i] = lb; else s0[i] = lb;
;     }
; template <int MODE>
; DI void attn_item(const Params& p, int layer, int b, int head, int qblk, u16* sm, volatile LAS int* s_done_, int wv) {
;     ...
;               f32x16 sa[2];
; #pragma unroll
;               for (int e = 0; e < 16; ++e) { sa[0][e] = 0.f; sa[1][e] = 0.f; }
; #pragma unroll
;               for (int t = 0; t < 2; ++t)
; #pragma unroll
;                 for (int ks = 0; ks < 4; ++ks) {
;                   bf16x8 kf = ldsv(Kc + (32 * t + r) * LSTR + ks * 16 + 8 * h);
;                   sa[t] = mfma(kf, qf[ks], sa[t]);
;                 }
;               stick_pv(sa[0], sa[1], R, o[0], o[1], Vc, dl, need_mask, r, h);
.LBB0_228:
	s_xor_b32 s2, s87, 0x3fffffd
	v_add_lshl_u32 v0, s2, v173, 6
	v_cmp_lt_i32_e64 s[2:3], v0, v176
	v_cmp_eq_u32_e64 s[40:41], 0, v64
	s_and_b64 s[2:3], s[2:3], s[40:41]
	s_and_saveexec_b64 s[18:19], s[2:3]
	s_cbranch_execz .LBB0_230
	v_or_b32_e32 v14, 63, v0
	v_cmp_lt_i32_e64 s[40:41], v14, v148
	v_add_u32_e32 v14, v152, v181
	s_waitcnt vmcnt(3)
	s_waitcnt vmcnt(2)
	ds_read_b128 v[48:51], v14 offset:36864
	ds_read_b128 v[52:55], v14 offset:36896
	ds_read_b128 v[240:243], v14 offset:36928
	ds_read_b128 v[244:247], v14 offset:36960
	ds_read_b128 v[204:207], v14 offset:41504
	v_or_b32_e32 v0, v0, v177
	s_waitcnt lgkmcnt(4)
	v_mfma_f32_32x32x16_bf16 v[64:79], v[48:51], v[88:91], 0
	v_sub_u32_e32 v0, v149, v0
	v_cmp_lt_i32_e64 s[2:3], 0, v0
	s_or_b64 s[2:3], s[40:41], s[2:3]
	v_add_f32_e32 v236, 0, v184
	s_waitcnt lgkmcnt(3)
	v_mfma_f32_32x32x16_bf16 v[64:79], v[52:55], v[80:83], v[64:79]
	s_waitcnt lgkmcnt(2)
	v_mfma_f32_32x32x16_bf16 v[64:79], v[240:243], v[84:87], v[64:79]
	ds_read_b128 v[240:243], v14 offset:41472
	s_waitcnt lgkmcnt(2)
	v_mfma_f32_32x32x16_bf16 v[64:79], v[244:247], v[92:95], v[64:79]
	ds_read_b128 v[244:247], v14 offset:41536
	s_waitcnt vmcnt(0) lgkmcnt(1)
	v_mfma_f32_32x32x16_bf16 v[48:63], v[240:243], v[88:91], 0
	ds_read_b128 v[240:243], v14 offset:41568
	v_mfma_f32_32x32x16_bf16 v[48:63], v[204:207], v[80:83], v[48:63]
	s_waitcnt lgkmcnt(1)
	v_mfma_f32_32x32x16_bf16 v[48:63], v[244:247], v[84:87], v[48:63]
	s_nop 3
	v_med3_f32 v14, v64, s94, v198
	v_exp_f32_e64 v15, -v14
	s_nop 0
	v_add_f32_e32 v15, 1.0, v15
	v_log_f32_e32 v15, v15
	s_waitcnt lgkmcnt(0)
	v_mfma_f32_32x32x16_bf16 v[48:63], v[240:243], v[92:95], v[48:63]
	v_sub_f32_e64 v14, -v15, v14
	v_cndmask_b32_e64 v165, v199, -v15, s[2:3]
	v_med3_f32 v15, v65, s94, v198
	v_exp_f32_e64 v64, -v15
	v_cndmask_b32_e64 v14, 0, v14, s[2:3]
	v_cmp_lt_i32_e64 s[2:3], 1, v0
	s_or_b64 s[2:3], s[40:41], s[2:3]
	v_add_f32_e32 v64, 1.0, v64
	v_log_f32_e32 v65, v64
	s_nop 2
	v_med3_f32 v48, v48, s94, v198
	v_sub_f32_e64 v15, -v65, v15
	v_cndmask_b32_e64 v64, 0, v15, s[2:3]
	v_med3_f32 v15, v66, s94, v198
	v_cndmask_b32_e64 v185, v199, -v65, s[2:3]
	v_exp_f32_e64 v65, -v15
	v_cmp_lt_i32_e64 s[2:3], 2, v0
	s_or_b64 s[2:3], s[40:41], s[2:3]
	v_add_f32_e32 v65, 1.0, v65
	v_log_f32_e32 v65, v65
	s_nop 0
	v_sub_f32_e64 v15, -v65, v15
	v_cndmask_b32_e64 v66, 0, v15, s[2:3]
	v_med3_f32 v15, v67, s94, v198
	v_cndmask_b32_e64 v186, v199, -v65, s[2:3]
	v_exp_f32_e64 v65, -v15
	v_cmp_lt_i32_e64 s[2:3], 3, v0
	s_or_b64 s[2:3], s[40:41], s[2:3]
	v_add_f32_e32 v65, 1.0, v65
	v_log_f32_e32 v65, v65
	s_nop 0
	v_sub_f32_e64 v15, -v65, v15
	v_cndmask_b32_e64 v166, 0, v15, s[2:3]
	v_med3_f32 v15, v68, s94, v198
	v_cndmask_b32_e64 v204, v199, -v65, s[2:3]
	v_exp_f32_e64 v65, -v15
	v_cmp_lt_i32_e64 s[2:3], 8, v0
	s_or_b64 s[2:3], s[40:41], s[2:3]
	v_add_f32_e32 v65, 1.0, v65
	v_log_f32_e32 v65, v65
	s_nop 0
	v_sub_f32_e64 v15, -v65, v15
	v_cndmask_b32_e64 v205, v199, -v65, s[2:3]
	v_med3_f32 v65, v69, s94, v198
	v_exp_f32_e64 v67, -v65
	v_cndmask_b32_e64 v15, 0, v15, s[2:3]
	v_cmp_lt_i32_e64 s[2:3], 9, v0
	s_or_b64 s[2:3], s[40:41], s[2:3]
	v_add_f32_e32 v67, 1.0, v67
	v_log_f32_e32 v67, v67
	s_nop 0
	v_sub_f32_e64 v65, -v67, v65
	v_cndmask_b32_e64 v207, 0, v65, s[2:3]
	v_med3_f32 v65, v70, s94, v198
	v_cndmask_b32_e64 v206, v199, -v67, s[2:3]
	v_exp_f32_e64 v67, -v65
	v_cmp_lt_i32_e64 s[2:3], 10, v0
	s_or_b64 s[2:3], s[40:41], s[2:3]
	v_add_f32_e32 v67, 1.0, v67
	v_log_f32_e32 v67, v67
	s_nop 0
	v_sub_f32_e64 v65, -v67, v65
	v_cndmask_b32_e64 v209, 0, v65, s[2:3]
	v_med3_f32 v65, v71, s94, v198
	v_cndmask_b32_e64 v208, v199, -v67, s[2:3]
	v_exp_f32_e64 v67, -v65
	v_cmp_lt_i32_e64 s[2:3], 11, v0
	s_or_b64 s[2:3], s[40:41], s[2:3]
	v_add_f32_e32 v67, 1.0, v67
	v_log_f32_e32 v67, v67
	s_nop 0
	v_sub_f32_e64 v65, -v67, v65
	v_cndmask_b32_e64 v211, 0, v65, s[2:3]
	v_med3_f32 v65, v72, s94, v198
	v_cndmask_b32_e64 v210, v199, -v67, s[2:3]
	v_exp_f32_e64 v67, -v65
	v_cmp_lt_i32_e64 s[2:3], 16, v0
	s_or_b64 s[2:3], s[40:41], s[2:3]
	v_add_f32_e32 v67, 1.0, v67
	v_log_f32_e32 v68, v67
	s_nop 0
	v_sub_f32_e64 v65, -v68, v65
	v_cndmask_b32_e64 v67, 0, v65, s[2:3]
	v_med3_f32 v65, v73, s94, v198
	v_cndmask_b32_e64 v212, v199, -v68, s[2:3]
	v_exp_f32_e64 v68, -v65
	v_cmp_lt_i32_e64 s[2:3], 17, v0
	s_or_b64 s[2:3], s[40:41], s[2:3]
	v_add_f32_e32 v68, 1.0, v68
	v_log_f32_e32 v68, v68
	s_nop 0
	v_sub_f32_e64 v65, -v68, v65
	v_cndmask_b32_e64 v214, 0, v65, s[2:3]
	v_med3_f32 v65, v74, s94, v198
	v_cndmask_b32_e64 v213, v199, -v68, s[2:3]
	v_exp_f32_e64 v68, -v65
	v_cmp_lt_i32_e64 s[2:3], 18, v0
	s_or_b64 s[2:3], s[40:41], s[2:3]
	v_add_f32_e32 v68, 1.0, v68
	v_log_f32_e32 v68, v68
	s_nop 0
	v_sub_f32_e64 v65, -v68, v65
	v_cndmask_b32_e64 v216, 0, v65, s[2:3]
	v_med3_f32 v65, v75, s94, v198
	v_cndmask_b32_e64 v215, v199, -v68, s[2:3]
	v_exp_f32_e64 v68, -v65
	v_cmp_lt_i32_e64 s[2:3], 19, v0
	s_or_b64 s[2:3], s[40:41], s[2:3]
	v_add_f32_e32 v68, 1.0, v68
	v_log_f32_e32 v68, v68
	s_nop 0
	v_sub_f32_e64 v65, -v68, v65
	v_cndmask_b32_e64 v218, 0, v65, s[2:3]
	v_med3_f32 v65, v76, s94, v198
	v_cndmask_b32_e64 v217, v199, -v68, s[2:3]
	v_exp_f32_e64 v68, -v65
	v_cmp_lt_i32_e64 s[2:3], 24, v0
	s_or_b64 s[2:3], s[40:41], s[2:3]
	v_add_f32_e32 v68, 1.0, v68
	v_log_f32_e32 v68, v68
	s_nop 0
	v_sub_f32_e64 v65, -v68, v65
	v_cndmask_b32_e64 v70, 0, v65, s[2:3]
	v_med3_f32 v65, v77, s94, v198
	v_cndmask_b32_e64 v76, v199, -v68, s[2:3]
	v_exp_f32_e64 v68, -v65
	v_cmp_lt_i32_e64 s[2:3], 25, v0
	s_or_b64 s[2:3], s[40:41], s[2:3]
	v_add_f32_e32 v68, 1.0, v68
	v_log_f32_e32 v69, v68
	s_nop 0
	v_sub_f32_e64 v65, -v69, v65
; DI float ex2(float x) { return __builtin_amdgcn_exp2f(x); }
; DI float lg2(float x) { return __builtin_amdgcn_logf(x); }
; DI void stick_pv(f32x16& s0, f32x16& s1, float& R, f32x16& o0, f32x16& o1, const u16* Vs, int dl,
;                  bool need_mask, int r, int h) {
;     ...
;     for (int i = 0; i < 16; ++i) {
;       const int ci = 32 * t + (i & 3) + 8 * (i >> 2);
;       float a = t ? s1[i] : s0[i];
;       float z = __builtin_amdgcn_fmed3f(a, -126.f, 126.f);
;       float e = ex2(-z);
;       float lb = -lg2(1.f + e);
;       float xi = lb - z;
;       if (need_mask) {
;         bool valid = (ci < dl);
;         xi = valid ? xi : 0.f;
;         lb = valid ? lb : -INFINITY;
;       }
;       x[16 * t + i] = xi;
;       if (t) s1[i] = lb; else s0[i] = lb;
;     }
;   float gs[8], pg[8], pr[8];
; #pragma unroll
;   for (int g = 0; g < 8; ++g) {
;     gs[g] = (x[4 * g] + x[4 * g + 1]) + (x[4 * g + 2] + x[4 * g + 3]);
;     pg[g] = shx(gs[g], r + 32 * h);
;     pr[g] = gs[g] + pg[g];
	v_cndmask_b32_e64 v68, 0, v65, s[2:3]
	v_med3_f32 v65, v78, s94, v198
	v_cndmask_b32_e64 v77, v199, -v69, s[2:3]
	v_exp_f32_e64 v69, -v65
	v_cmp_lt_i32_e64 s[2:3], 26, v0
	s_or_b64 s[2:3], s[40:41], s[2:3]
	v_add_f32_e32 v69, 1.0, v69
	v_log_f32_e32 v69, v69
	s_nop 0
	v_sub_f32_e64 v65, -v69, v65
	v_cndmask_b32_e64 v72, 0, v65, s[2:3]
	v_med3_f32 v65, v79, s94, v198
	v_cndmask_b32_e64 v78, v199, -v69, s[2:3]
	v_exp_f32_e64 v69, -v65
	v_cmp_lt_i32_e64 s[2:3], 27, v0
	s_or_b64 s[2:3], s[40:41], s[2:3]
	v_add_f32_e32 v69, 1.0, v69
	v_log_f32_e32 v69, v69
	s_nop 0
	v_sub_f32_e64 v65, -v69, v65
	v_cndmask_b32_e64 v74, 0, v65, s[2:3]
	v_exp_f32_e64 v65, -v48
	v_cndmask_b32_e64 v79, v199, -v69, s[2:3]
	v_cmp_lt_i32_e64 s[2:3], 32, v0
	s_or_b64 s[2:3], s[40:41], s[2:3]
	v_add_f32_e32 v65, 1.0, v65
	v_log_f32_e32 v65, v65
	s_nop 0
	v_sub_f32_e64 v48, -v65, v48
	v_cndmask_b32_e64 v69, 0, v48, s[2:3]
	v_med3_f32 v48, v49, s94, v198
	v_exp_f32_e64 v49, -v48
	v_cndmask_b32_e64 v167, v199, -v65, s[2:3]
	v_cmp_lt_i32_e64 s[2:3], 33, v0
	s_or_b64 s[2:3], s[40:41], s[2:3]
	v_add_f32_e32 v49, 1.0, v49
	v_log_f32_e32 v49, v49
	s_nop 0
	v_sub_f32_e64 v48, -v49, v48
	v_cndmask_b32_e64 v220, 0, v48, s[2:3]
	v_med3_f32 v48, v50, s94, v198
	v_cndmask_b32_e64 v219, v199, -v49, s[2:3]
	v_exp_f32_e64 v49, -v48
	v_cmp_lt_i32_e64 s[2:3], 34, v0
	s_or_b64 s[2:3], s[40:41], s[2:3]
	v_add_f32_e32 v49, 1.0, v49
	v_log_f32_e32 v49, v49
	s_nop 0
	v_sub_f32_e64 v48, -v49, v48
	v_cndmask_b32_e64 v222, 0, v48, s[2:3]
	v_med3_f32 v48, v51, s94, v198
	v_cndmask_b32_e64 v221, v199, -v49, s[2:3]
	v_exp_f32_e64 v49, -v48
	v_cmp_lt_i32_e64 s[2:3], 35, v0
	s_or_b64 s[2:3], s[40:41], s[2:3]
	v_add_f32_e32 v49, 1.0, v49
	v_log_f32_e32 v49, v49
	s_nop 0
	v_sub_f32_e64 v48, -v49, v48
	v_cndmask_b32_e64 v224, 0, v48, s[2:3]
	v_med3_f32 v48, v52, s94, v198
	v_cndmask_b32_e64 v223, v199, -v49, s[2:3]
	v_exp_f32_e64 v49, -v48
	v_cmp_lt_i32_e64 s[2:3], 40, v0
	s_or_b64 s[2:3], s[40:41], s[2:3]
	v_add_f32_e32 v49, 1.0, v49
	v_log_f32_e32 v49, v49
	s_nop 0
	v_sub_f32_e64 v48, -v49, v48
	v_cndmask_b32_e64 v51, 0, v48, s[2:3]
	v_med3_f32 v48, v53, s94, v198
	v_cndmask_b32_e64 v52, v199, -v49, s[2:3]
	v_exp_f32_e64 v49, -v48
	v_cmp_lt_i32_e64 s[2:3], 41, v0
	s_or_b64 s[2:3], s[40:41], s[2:3]
	v_add_f32_e32 v49, 1.0, v49
	v_log_f32_e32 v49, v49
	s_nop 0
	v_sub_f32_e64 v48, -v49, v48
	v_cndmask_b32_e64 v53, 0, v48, s[2:3]
	v_med3_f32 v48, v54, s94, v198
	v_cndmask_b32_e64 v75, v199, -v49, s[2:3]
	v_exp_f32_e64 v49, -v48
	v_cmp_lt_i32_e64 s[2:3], 42, v0
	s_or_b64 s[2:3], s[40:41], s[2:3]
	v_add_f32_e32 v49, 1.0, v49
	v_log_f32_e32 v49, v49
	s_nop 0
	v_sub_f32_e64 v48, -v49, v48
	v_cndmask_b32_e64 v225, 0, v48, s[2:3]
	v_med3_f32 v48, v55, s94, v198
	v_cndmask_b32_e64 v226, v199, -v49, s[2:3]
	v_exp_f32_e64 v49, -v48
	v_cmp_lt_i32_e64 s[2:3], 43, v0
	s_or_b64 s[2:3], s[40:41], s[2:3]
	v_add_f32_e32 v49, 1.0, v49
	v_log_f32_e32 v49, v49
	s_nop 0
	v_sub_f32_e64 v48, -v49, v48
	v_cndmask_b32_e64 v227, 0, v48, s[2:3]
	v_med3_f32 v48, v56, s94, v198
	v_cndmask_b32_e64 v228, v199, -v49, s[2:3]
	v_exp_f32_e64 v49, -v48
	v_cmp_lt_i32_e64 s[2:3], 48, v0
	s_or_b64 s[2:3], s[40:41], s[2:3]
	v_add_f32_e32 v49, 1.0, v49
	v_log_f32_e32 v49, v49
	s_nop 0
	v_sub_f32_e64 v48, -v49, v48
	v_cndmask_b32_e64 v56, v199, -v49, s[2:3]
	v_med3_f32 v49, v57, s94, v198
	v_exp_f32_e64 v50, -v49
	v_cndmask_b32_e64 v48, 0, v48, s[2:3]
	v_cmp_lt_i32_e64 s[2:3], 49, v0
	s_or_b64 s[2:3], s[40:41], s[2:3]
	v_add_f32_e32 v50, 1.0, v50
	v_log_f32_e32 v54, v50
	s_nop 0
	v_sub_f32_e64 v49, -v54, v49
	v_cndmask_b32_e64 v50, 0, v49, s[2:3]
	v_med3_f32 v49, v58, s94, v198
	v_cndmask_b32_e64 v57, v199, -v54, s[2:3]
	v_exp_f32_e64 v54, -v49
	v_cmp_lt_i32_e64 s[2:3], 50, v0
	s_or_b64 s[2:3], s[40:41], s[2:3]
	v_add_f32_e32 v54, 1.0, v54
	v_log_f32_e32 v54, v54
	s_nop 0
	v_sub_f32_e64 v49, -v54, v49
	v_cndmask_b32_e64 v58, 0, v49, s[2:3]
	v_med3_f32 v49, v59, s94, v198
	v_cndmask_b32_e64 v229, v199, -v54, s[2:3]
	v_exp_f32_e64 v54, -v49
	v_cmp_lt_i32_e64 s[2:3], 51, v0
	s_or_b64 s[2:3], s[40:41], s[2:3]
	v_add_f32_e32 v54, 1.0, v54
	v_log_f32_e32 v54, v54
	s_nop 0
	v_sub_f32_e64 v49, -v54, v49
	v_cndmask_b32_e64 v59, 0, v49, s[2:3]
	v_med3_f32 v49, v60, s94, v198
	v_cndmask_b32_e64 v230, v199, -v54, s[2:3]
	v_exp_f32_e64 v54, -v49
	v_cmp_lt_i32_e64 s[2:3], 56, v0
	s_or_b64 s[2:3], s[40:41], s[2:3]
	v_add_f32_e32 v54, 1.0, v54
	v_log_f32_e32 v54, v54
	s_nop 0
	v_sub_f32_e64 v49, -v54, v49
	v_cndmask_b32_e64 v60, v199, -v54, s[2:3]
	v_med3_f32 v54, v61, s94, v198
	v_exp_f32_e64 v55, -v54
	v_cndmask_b32_e64 v49, 0, v49, s[2:3]
	v_cmp_lt_i32_e64 s[2:3], 57, v0
	s_or_b64 s[2:3], s[40:41], s[2:3]
	v_add_f32_e32 v55, 1.0, v55
	v_log_f32_e32 v55, v55
	s_nop 0
	v_sub_f32_e64 v54, -v55, v54
	v_cndmask_b32_e64 v61, 0, v54, s[2:3]
	v_med3_f32 v54, v62, s94, v198
	v_cndmask_b32_e64 v231, v199, -v55, s[2:3]
	v_exp_f32_e64 v55, -v54
	v_cmp_lt_i32_e64 s[2:3], 58, v0
	s_or_b64 s[2:3], s[40:41], s[2:3]
	v_add_f32_e32 v49, v49, v61
	v_add_f32_e32 v55, 1.0, v55
	v_log_f32_e32 v55, v55
	s_nop 0
	v_sub_f32_e64 v54, -v55, v54
	v_cndmask_b32_e64 v62, 0, v54, s[2:3]
	v_med3_f32 v54, v63, s94, v198
	v_cndmask_b32_e64 v232, v199, -v55, s[2:3]
	v_exp_f32_e64 v55, -v54
	v_cmp_lt_i32_e64 s[2:3], 59, v0
	s_or_b64 s[2:3], s[40:41], s[2:3]
	v_add_f32_e32 v0, v15, v207
	v_add_f32_e32 v55, 1.0, v55
	v_log_f32_e32 v55, v55
	v_add_f32_e32 v15, v209, v211
	v_add_f32_e32 v15, v0, v15
	v_add_f32_e32 v0, v67, v214
	v_sub_f32_e64 v54, -v55, v54
	v_cndmask_b32_e64 v63, 0, v54, s[2:3]
	v_add_f32_e32 v54, v216, v218
	v_add_f32_e32 v0, v0, v54
	ds_bpermute_b32 v234, v180, v0
	v_add_f32_e32 v54, v222, v224
	v_cndmask_b32_e64 v233, v199, -v55, s[2:3]
	ds_bpermute_b32 v65, v180, v15
	s_mov_b32 s2, 0xc3200000
	s_waitcnt lgkmcnt(1)
; DI float ex2(float x) { return __builtin_amdgcn_exp2f(x); }
; DI f32x16 mfma(bf16x8 a, bf16x8 b, f32x16 c) { return __builtin_amdgcn_mfma_f32_32x32x16_bf16(a, b, c, 0, 0, 0); }
; DI void stick_pv(f32x16& s0, f32x16& s1, float& R, f32x16& o0, f32x16& o1, const u16* Vs, int dl,
;                  bool need_mask, int r, int h) {
;     ...
;   float gs[8], pg[8], pr[8];
; #pragma unroll
;   for (int g = 0; g < 8; ++g) {
;     gs[g] = (x[4 * g] + x[4 * g + 1]) + (x[4 * g + 2] + x[4 * g + 3]);
;     pg[g] = shx(gs[g], r + 32 * h);
;     pr[g] = gs[g] + pg[g];
;   }
;   float suf = 0.f;
; #pragma unroll
;   for (int g = 7; g >= 0; --g) {
;     float base = R + suf + (h == 0 ? pg[g] : 0.f);
;     float t3 = base, t2 = t3 + x[4 * g + 3], t1 = t2 + x[4 * g + 2], t0 = t1 + x[4 * g + 1];
;     const int i = 4 * (g & 3);
;     if (g >= 4) {
;       s1[i] = ex2(s1[i] + t0); s1[i + 1] = ex2(s1[i + 1] + t1); s1[i + 2] = ex2(s1[i + 2] + t2); s1[i + 3] = ex2(s1[i + 3] + t3);
;     } else {
;       s0[i] = ex2(s0[i] + t0); s0[i + 1] = ex2(s0[i + 1] + t1); s0[i + 2] = ex2(s0[i + 2] + t2); s0[i + 3] = ex2(s0[i + 3] + t3);
;     }
;     suf += pr[g];
;   }
;   R += suf;
; #pragma unroll
;   for (int kk = 0; kk < 4; ++kk) {
;     const int s = kk & 1;
;     unsigned u0, u1, u2, u3;
;     if (kk < 2) {
;       u0 = pk2(s0[8 * s], s0[8 * s + 1]); u1 = pk2(s0[8 * s + 2], s0[8 * s + 3]);
;       u2 = pk2(s0[8 * s + 4], s0[8 * s + 5]); u3 = pk2(s0[8 * s + 6], s0[8 * s + 7]);
;     } else {
;       u0 = pk2(s1[8 * s], s1[8 * s + 1]); u1 = pk2(s1[8 * s + 2], s1[8 * s + 3]);
;       u2 = pk2(s1[8 * s + 4], s1[8 * s + 5]); u3 = pk2(s1[8 * s + 6], s1[8 * s + 7]);
;     }
;     u32x4 uu = {u0, u1, u2, u3};
;     bf16x8 pf = __builtin_bit_cast(bf16x8, uu);
;     bf16x8 v0 = ldsv(Vs + r * LSTR + kk * 16 + 8 * h);
;     bf16x8 v1 = ldsv(Vs + (32 + r) * LSTR + kk * 16 + 8 * h);
;     o0 = mfma(v0, pf, o0);
;     o1 = mfma(v1, pf, o1);
;   }
; template <int MODE>
; DI void attn_item(const Params& p, int layer, int b, int head, int qblk, u16* sm, volatile LAS int* s_done_, int wv) {
;     ...
;               wdone = __all(R < -160.f) ? 1 : 0;
	v_add_f32_e32 v67, v0, v234
	v_add_f32_e32 v0, v69, v220
	v_add_f32_e32 v71, v0, v54
	v_add_f32_e32 v0, v51, v53
	v_add_f32_e32 v51, v225, v227
	v_add_f32_e32 v0, v0, v51
	v_add_f32_e32 v51, v62, v63
	v_add_f32_e32 v48, v48, v50
	v_add_f32_e32 v49, v49, v51
	ds_bpermute_b32 v55, v180, v49
	ds_bpermute_b32 v235, v180, v0
	v_add_f32_e32 v54, v58, v59
	ds_bpermute_b32 v69, v180, v71
	s_waitcnt lgkmcnt(3)
	v_add_f32_e32 v14, v14, v64
	v_add_f32_e32 v15, v15, v65
	s_waitcnt lgkmcnt(2)
	v_add_f32_e32 v48, v48, v54
	v_add_f32_e32 v49, v49, v55
	s_waitcnt lgkmcnt(1)
	v_add_f32_e32 v73, v0, v235
	ds_bpermute_b32 v0, v180, v48
	v_cndmask_b32_e32 v51, 0, v55, vcc
	v_add_f32_e32 v51, v236, v51
	v_add_f32_e32 v54, v63, v51
	v_add_f32_e32 v51, v233, v51
	s_waitcnt lgkmcnt(0)
	v_add_f32_e32 v48, v48, v0
	v_add_f32_e32 v49, v49, v1
	v_exp_f32_e32 v233, v51
	v_add_f32_e32 v51, v184, v49
	v_cndmask_b32_e32 v0, 0, v0, vcc
	v_add_f32_e32 v0, v0, v51
	v_add_f32_e32 v55, v62, v54
	v_add_f32_e32 v54, v232, v54
	v_add_f32_e32 v51, v59, v0
	v_exp_f32_e32 v232, v54
	v_add_f32_e32 v54, v58, v51
	v_add_f32_e32 v50, v50, v54
	v_add_f32_e32 v50, v56, v50
	v_exp_f32_e32 v237, v50
	v_add_f32_e32 v50, v57, v54
	v_exp_f32_e32 v238, v50
	v_add_f32_e32 v50, v229, v51
	v_pk_add_f32 v[48:49], v[48:49], v[48:49] op_sel:[0,1] op_sel_hi:[1,0]
	v_exp_f32_e32 v229, v50
	v_add_f32_e32 v49, v184, v48
	v_cndmask_b32_e32 v50, 0, v235, vcc
	v_add_f32_e32 v49, v50, v49
	v_add_f32_e32 v50, v227, v49
	v_add_f32_e32 v51, v225, v50
	v_add_f32_e32 v53, v53, v51
	v_add_f32_e32 v51, v75, v51
	v_add_f32_e32 v50, v226, v50
	v_add_f32_e32 v49, v228, v49
	v_mov_b32_e32 v75, v48
	v_exp_f32_e32 v227, v51
	v_exp_f32_e32 v226, v50
	v_exp_f32_e32 v228, v49
	v_add_f32_e32 v50, v70, v68
	v_add_f32_e32 v51, v71, v69
	v_add_f32_e32 v48, v72, v74
	v_add_f32_e32 v49, v73, v75
	v_add_f32_e32 v52, v52, v53
	v_add_f32_e32 v50, v50, v48
	v_add_f32_e32 v51, v51, v49
	ds_bpermute_b32 v48, v180, v50
	v_exp_f32_e32 v225, v52
	v_cndmask_b32_e32 v52, 0, v69, vcc
	v_add_f32_e32 v49, v184, v49
	v_add_f32_e32 v49, v52, v49
	v_add_f32_e32 v52, v224, v49
	v_add_f32_e32 v49, v223, v49
	s_waitcnt lgkmcnt(0)
	v_add_f32_e32 v50, v50, v48
	v_exp_f32_e32 v73, v49
	v_add_f32_e32 v49, v184, v51
	v_cndmask_b32_e32 v48, 0, v48, vcc
	v_add_f32_e32 v53, v222, v52
	v_add_f32_e32 v48, v48, v49
	v_add_f32_e32 v54, v220, v53
	v_add_f32_e32 v52, v221, v52
	v_add_f32_e32 v49, v74, v48
	v_add_f32_e32 v54, v167, v54
	v_exp_f32_e32 v71, v52
	v_add_f32_e32 v52, v72, v49
	v_add_f32_e32 v49, v78, v49
	v_add_f32_e32 v48, v79, v48
	v_add_f32_e32 v167, v50, v51
	v_exp_f32_e32 v74, v49
	v_exp_f32_e32 v75, v48
	v_add_f32_e32 v48, v184, v167
	v_cndmask_b32_e32 v49, 0, v234, vcc
	v_add_f32_e32 v48, v49, v48
	v_add_f32_e32 v49, v218, v48
	v_add_f32_e32 v50, v216, v49
	v_add_f32_e32 v49, v215, v49
	v_add_f32_e32 v48, v217, v48
	v_exp_f32_e32 v78, v49
	v_exp_f32_e32 v79, v48
	v_add_f32_e32 v48, v66, v166
	v_add_f32_e32 v49, v67, v167
	v_add_f32_e32 v53, v219, v53
	v_add_f32_e32 v51, v214, v50
	v_add_f32_e32 v50, v213, v50
	v_add_f32_e32 v14, v14, v48
	v_add_f32_e32 v15, v15, v49
	v_exp_f32_e32 v70, v53
	v_add_f32_e32 v53, v68, v52
	v_add_f32_e32 v52, v77, v52
	v_exp_f32_e32 v77, v50
	v_cndmask_b32_e32 v50, 0, v65, vcc
	ds_bpermute_b32 v48, v180, v14
	v_add_f32_e32 v49, v184, v49
	v_add_f32_e32 v49, v50, v49
	v_add_f32_e32 v51, v212, v51
	v_add_f32_e32 v50, v211, v49
	v_add_f32_e32 v53, v76, v53
	v_exp_f32_e32 v76, v51
	v_add_f32_e32 v51, v209, v50
	v_exp_f32_e32 v72, v52
	v_add_f32_e32 v52, v207, v51
	v_add_f32_e32 v51, v206, v51
	v_exp_f32_e32 v68, v53
	s_waitcnt lgkmcnt(0)
	v_add_f32_e32 v14, v14, v48
	v_exp_f32_e32 v53, v51
	v_add_f32_e32 v51, v184, v15
	v_cndmask_b32_e32 v48, 0, v48, vcc
	v_add_f32_e32 v48, v48, v51
	v_add_f32_e32 v51, v166, v48
	v_add_f32_e32 v61, v61, v55
	v_add_f32_e32 v55, v231, v55
	v_exp_f32_e32 v69, v54
	v_add_f32_e32 v54, v66, v51
	v_exp_f32_e32 v231, v55
	v_add_f32_e32 v55, v64, v54
	v_add_f32_e32 v52, v205, v52
	v_add_f32_e32 v50, v208, v50
	v_add_f32_e32 v49, v210, v49
	v_add_f32_e32 v55, v165, v55
	v_add_f32_e32 v54, v185, v54
	v_add_f32_e32 v51, v186, v51
	v_add_f32_e32 v48, v204, v48
	v_exp_f32_e32 v52, v52
	v_exp_f32_e32 v50, v50
	v_exp_f32_e32 v49, v49
	v_exp_f32_e32 v55, v55
	v_exp_f32_e32 v54, v54
	v_exp_f32_e32 v56, v51
	v_exp_f32_e32 v48, v48
	v_add_f32_e32 v60, v60, v61
	v_exp_f32_e32 v236, v60
	v_cvt_pk_bf16_f32 v51, v50, v49
	v_cvt_pk_bf16_f32 v50, v52, v53
	v_cvt_pk_bf16_f32 v49, v56, v48
	v_cvt_pk_bf16_f32 v48, v55, v54
	ds_read_b128 v[52:55], v155 offset:50688
	ds_read_b128 v[56:59], v155 offset:46080
	ds_read_b128 v[60:63], v155 offset:46112
	s_waitcnt lgkmcnt(2)
	v_mfma_f32_32x32x16_bf16 v[16:31], v[52:55], v[48:51], v[16:31]
	ds_read_b128 v[52:55], v155 offset:50720
	v_add_f32_e32 v0, v230, v0
	v_exp_f32_e32 v0, v0
	v_add_f32_e32 v14, v14, v15
	v_add_f32_e32 v184, v184, v14
	v_cmp_gt_f32_e64 s[2:3], s2, v184
	s_cmp_eq_u64 s[2:3], exec
	s_waitcnt lgkmcnt(2)
	v_mfma_f32_32x32x16_bf16 v[32:47], v[56:59], v[48:51], v[32:47]
	v_cvt_pk_bf16_f32 v51, v74, v75
	v_cvt_pk_bf16_f32 v50, v68, v72
	v_cvt_pk_bf16_f32 v49, v78, v79
	v_cvt_pk_bf16_f32 v48, v76, v77
	s_cselect_b64 s[2:3], -1, 0
	v_cndmask_b32_e64 v64, 0, 1, s[2:3]
	s_waitcnt lgkmcnt(1)
	v_mfma_f32_32x32x16_bf16 v[32:47], v[60:63], v[48:51], v[32:47]
	s_waitcnt lgkmcnt(0)
	v_mfma_f32_32x32x16_bf16 v[16:31], v[52:55], v[48:51], v[16:31]
	ds_read_b128 v[52:55], v155 offset:46144
	ds_read_b128 v[56:59], v155 offset:50752
	v_cvt_pk_bf16_f32 v51, v226, v228
	v_cvt_pk_bf16_f32 v50, v225, v227
	v_cvt_pk_bf16_f32 v49, v71, v73
	v_cvt_pk_bf16_f32 v48, v69, v70
	s_waitcnt lgkmcnt(1)
	s_nop 0
	v_mfma_f32_32x32x16_bf16 v[32:47], v[52:55], v[48:51], v[32:47]
	s_waitcnt lgkmcnt(0)
	v_mfma_f32_32x32x16_bf16 v[16:31], v[56:59], v[48:51], v[16:31]
	ds_read_b128 v[52:55], v155 offset:46176
	ds_read_b128 v[56:59], v155 offset:50784
	v_cvt_pk_bf16_f32 v51, v232, v233
	v_cvt_pk_bf16_f32 v50, v236, v231
	v_cvt_pk_bf16_f32 v49, v229, v0
	v_cvt_pk_bf16_f32 v48, v237, v238
	s_waitcnt lgkmcnt(1)
	s_nop 0
	v_mfma_f32_32x32x16_bf16 v[32:47], v[52:55], v[48:51], v[32:47]
	s_waitcnt lgkmcnt(0)
	v_mfma_f32_32x32x16_bf16 v[16:31], v[56:59], v[48:51], v[16:31]

; DI float ex2(float x) { return __builtin_amdgcn_exp2f(x); }
; DI float lg2(float x) { return __builtin_amdgcn_logf(x); }
; DI f32x16 mfma(bf16x8 a, bf16x8 b, f32x16 c) { return __builtin_amdgcn_mfma_f32_32x32x16_bf16(a, b, c, 0, 0, 0); }
; DI void stick_pv(f32x16& s0, f32x16& s1, float& R, f32x16& o0, f32x16& o1, const u16* Vs, int dl,
;                  bool need_mask, int r, int h) {
;   float x[32];
; #pragma unroll
;   for (int t = 0; t < 2; ++t)
; #pragma unroll
;     for (int i = 0; i < 16; ++i) {
;       const int ci = 32 * t + (i & 3) + 8 * (i >> 2);
;       float a = t ? s1[i] : s0[i];
;       float z = __builtin_amdgcn_fmed3f(a, -126.f, 126.f);
;       float e = ex2(-z);
;       float lb = -lg2(1.f + e);
;       float xi = lb - z;
;       if (need_mask) {
;         bool valid = (ci < dl);
;         xi = valid ? xi : 0.f;
;         lb = valid ? lb : -INFINITY;
;       }
;       x[16 * t + i] = xi;
;       if (t) s1[i] = lb; else s0[i] = lb;
;     }
; template <int MODE>
; DI void attn_item(const Params& p, int layer, int b, int head, int qblk, u16* sm, volatile LAS int* s_done_, int wv) {
;     ...
;               f32x16 sa[2];
; #pragma unroll
;               for (int e = 0; e < 16; ++e) { sa[0][e] = 0.f; sa[1][e] = 0.f; }
; #pragma unroll
;               for (int t = 0; t < 2; ++t)
; #pragma unroll
;                 for (int ks = 0; ks < 4; ++ks) {
;                   bf16x8 kf = ldsv(Kc + (32 * t + r) * LSTR + ks * 16 + 8 * h);
;                   sa[t] = mfma(kf, qf[ks], sa[t]);
;                 }
;               stick_pv(sa[0], sa[1], R, o[0], o[1], Vc, dl, need_mask, r, h);
.LBB0_235:
	s_xor_b32 s2, s87, 0x3fffffe
	v_add_lshl_u32 v0, s2, v173, 6
	v_cmp_lt_i32_e64 s[2:3], v0, v176
	v_cmp_eq_u32_e64 s[42:43], 0, v64
	s_and_b64 s[2:3], s[2:3], s[42:43]
	s_and_saveexec_b64 s[18:19], s[2:3]
	s_cbranch_execz .LBB0_237
	v_or_b32_e32 v14, 63, v0
	v_cmp_lt_i32_e64 s[42:43], v14, v148
	v_add_u32_e32 v14, v152, v181
	s_waitcnt vmcnt(3)
	s_waitcnt vmcnt(2)
	ds_read_b128 v[48:51], v14 offset:18432
	ds_read_b128 v[52:55], v14 offset:18464
	ds_read_b128 v[240:243], v14 offset:18496
	ds_read_b128 v[244:247], v14 offset:18528
	ds_read_b128 v[204:207], v14 offset:23072
	v_or_b32_e32 v0, v0, v177
	s_waitcnt lgkmcnt(4)
	v_mfma_f32_32x32x16_bf16 v[64:79], v[48:51], v[88:91], 0
	v_sub_u32_e32 v0, v149, v0
	v_cmp_lt_i32_e64 s[2:3], 0, v0
	s_or_b64 s[2:3], s[42:43], s[2:3]
	v_add_f32_e32 v236, 0, v184
	s_waitcnt lgkmcnt(3)
	v_mfma_f32_32x32x16_bf16 v[64:79], v[52:55], v[80:83], v[64:79]
	s_waitcnt lgkmcnt(2)
	v_mfma_f32_32x32x16_bf16 v[64:79], v[240:243], v[84:87], v[64:79]
	ds_read_b128 v[240:243], v14 offset:23040
	s_waitcnt lgkmcnt(2)
	v_mfma_f32_32x32x16_bf16 v[64:79], v[244:247], v[92:95], v[64:79]
	ds_read_b128 v[244:247], v14 offset:23104
	s_waitcnt vmcnt(0) lgkmcnt(1)
	v_mfma_f32_32x32x16_bf16 v[48:63], v[240:243], v[88:91], 0
	ds_read_b128 v[240:243], v14 offset:23136
	v_mfma_f32_32x32x16_bf16 v[48:63], v[204:207], v[80:83], v[48:63]
	s_waitcnt lgkmcnt(1)
	v_mfma_f32_32x32x16_bf16 v[48:63], v[244:247], v[84:87], v[48:63]
	s_nop 3
	v_med3_f32 v14, v64, s94, v198
	v_exp_f32_e64 v15, -v14
	s_nop 0
	v_add_f32_e32 v15, 1.0, v15
	v_log_f32_e32 v15, v15
	s_waitcnt lgkmcnt(0)
	v_mfma_f32_32x32x16_bf16 v[48:63], v[240:243], v[92:95], v[48:63]
	v_sub_f32_e64 v14, -v15, v14
	v_cndmask_b32_e64 v165, v199, -v15, s[2:3]
	v_med3_f32 v15, v65, s94, v198
	v_exp_f32_e64 v64, -v15
	v_cndmask_b32_e64 v14, 0, v14, s[2:3]
	v_cmp_lt_i32_e64 s[2:3], 1, v0
	s_or_b64 s[2:3], s[42:43], s[2:3]
	v_add_f32_e32 v64, 1.0, v64
	v_log_f32_e32 v65, v64
	s_nop 2
	v_med3_f32 v48, v48, s94, v198
	v_sub_f32_e64 v15, -v65, v15
	v_cndmask_b32_e64 v64, 0, v15, s[2:3]
	v_med3_f32 v15, v66, s94, v198
	v_cndmask_b32_e64 v185, v199, -v65, s[2:3]
	v_exp_f32_e64 v65, -v15
	v_cmp_lt_i32_e64 s[2:3], 2, v0
	s_or_b64 s[2:3], s[42:43], s[2:3]
	v_add_f32_e32 v65, 1.0, v65
	v_log_f32_e32 v65, v65
	s_nop 0
	v_sub_f32_e64 v15, -v65, v15
	v_cndmask_b32_e64 v66, 0, v15, s[2:3]
	v_med3_f32 v15, v67, s94, v198
	v_cndmask_b32_e64 v186, v199, -v65, s[2:3]
	v_exp_f32_e64 v65, -v15
	v_cmp_lt_i32_e64 s[2:3], 3, v0
	s_or_b64 s[2:3], s[42:43], s[2:3]
	v_add_f32_e32 v65, 1.0, v65
	v_log_f32_e32 v65, v65
	s_nop 0
	v_sub_f32_e64 v15, -v65, v15
	v_cndmask_b32_e64 v166, 0, v15, s[2:3]
	v_med3_f32 v15, v68, s94, v198
	v_cndmask_b32_e64 v204, v199, -v65, s[2:3]
	v_exp_f32_e64 v65, -v15
	v_cmp_lt_i32_e64 s[2:3], 8, v0
	s_or_b64 s[2:3], s[42:43], s[2:3]
	v_add_f32_e32 v65, 1.0, v65
	v_log_f32_e32 v65, v65
	s_nop 0
	v_sub_f32_e64 v15, -v65, v15
	v_cndmask_b32_e64 v205, v199, -v65, s[2:3]
	v_med3_f32 v65, v69, s94, v198
	v_exp_f32_e64 v67, -v65
	v_cndmask_b32_e64 v15, 0, v15, s[2:3]
	v_cmp_lt_i32_e64 s[2:3], 9, v0
	s_or_b64 s[2:3], s[42:43], s[2:3]
	v_add_f32_e32 v67, 1.0, v67
	v_log_f32_e32 v67, v67
	s_nop 0
	v_sub_f32_e64 v65, -v67, v65
	v_cndmask_b32_e64 v207, 0, v65, s[2:3]
	v_med3_f32 v65, v70, s94, v198
	v_cndmask_b32_e64 v206, v199, -v67, s[2:3]
	v_exp_f32_e64 v67, -v65
	v_cmp_lt_i32_e64 s[2:3], 10, v0
	s_or_b64 s[2:3], s[42:43], s[2:3]
	v_add_f32_e32 v67, 1.0, v67
	v_log_f32_e32 v67, v67
	s_nop 0
	v_sub_f32_e64 v65, -v67, v65
	v_cndmask_b32_e64 v209, 0, v65, s[2:3]
	v_med3_f32 v65, v71, s94, v198
	v_cndmask_b32_e64 v208, v199, -v67, s[2:3]
	v_exp_f32_e64 v67, -v65
	v_cmp_lt_i32_e64 s[2:3], 11, v0
	s_or_b64 s[2:3], s[42:43], s[2:3]
	v_add_f32_e32 v67, 1.0, v67
	v_log_f32_e32 v67, v67
	s_nop 0
	v_sub_f32_e64 v65, -v67, v65
	v_cndmask_b32_e64 v211, 0, v65, s[2:3]
	v_med3_f32 v65, v72, s94, v198
	v_cndmask_b32_e64 v210, v199, -v67, s[2:3]
	v_exp_f32_e64 v67, -v65
	v_cmp_lt_i32_e64 s[2:3], 16, v0
	s_or_b64 s[2:3], s[42:43], s[2:3]
	v_add_f32_e32 v67, 1.0, v67
	v_log_f32_e32 v68, v67
	s_nop 0
	v_sub_f32_e64 v65, -v68, v65
	v_cndmask_b32_e64 v67, 0, v65, s[2:3]
	v_med3_f32 v65, v73, s94, v198
	v_cndmask_b32_e64 v212, v199, -v68, s[2:3]
	v_exp_f32_e64 v68, -v65
	v_cmp_lt_i32_e64 s[2:3], 17, v0
	s_or_b64 s[2:3], s[42:43], s[2:3]
	v_add_f32_e32 v68, 1.0, v68
	v_log_f32_e32 v68, v68
	s_nop 0
	v_sub_f32_e64 v65, -v68, v65
	v_cndmask_b32_e64 v214, 0, v65, s[2:3]
	v_med3_f32 v65, v74, s94, v198
	v_cndmask_b32_e64 v213, v199, -v68, s[2:3]
	v_exp_f32_e64 v68, -v65
	v_cmp_lt_i32_e64 s[2:3], 18, v0
	s_or_b64 s[2:3], s[42:43], s[2:3]
	v_add_f32_e32 v68, 1.0, v68
	v_log_f32_e32 v68, v68
	s_nop 0
	v_sub_f32_e64 v65, -v68, v65
	v_cndmask_b32_e64 v216, 0, v65, s[2:3]
	v_med3_f32 v65, v75, s94, v198
	v_cndmask_b32_e64 v215, v199, -v68, s[2:3]
	v_exp_f32_e64 v68, -v65
	v_cmp_lt_i32_e64 s[2:3], 19, v0
	s_or_b64 s[2:3], s[42:43], s[2:3]
	v_add_f32_e32 v68, 1.0, v68
	v_log_f32_e32 v68, v68
	s_nop 0
	v_sub_f32_e64 v65, -v68, v65
	v_cndmask_b32_e64 v218, 0, v65, s[2:3]
	v_med3_f32 v65, v76, s94, v198
	v_cndmask_b32_e64 v217, v199, -v68, s[2:3]
	v_exp_f32_e64 v68, -v65
	v_cmp_lt_i32_e64 s[2:3], 24, v0
	s_or_b64 s[2:3], s[42:43], s[2:3]
	v_add_f32_e32 v68, 1.0, v68
	v_log_f32_e32 v68, v68
	s_nop 0
	v_sub_f32_e64 v65, -v68, v65
	v_cndmask_b32_e64 v70, 0, v65, s[2:3]
	v_med3_f32 v65, v77, s94, v198
	v_cndmask_b32_e64 v76, v199, -v68, s[2:3]
	v_exp_f32_e64 v68, -v65
	v_cmp_lt_i32_e64 s[2:3], 25, v0
	s_or_b64 s[2:3], s[42:43], s[2:3]
	v_add_f32_e32 v68, 1.0, v68
	v_log_f32_e32 v69, v68
	s_nop 0
	v_sub_f32_e64 v65, -v69, v65
; DI float ex2(float x) { return __builtin_amdgcn_exp2f(x); }
; DI float lg2(float x) { return __builtin_amdgcn_logf(x); }
; DI void stick_pv(f32x16& s0, f32x16& s1, float& R, f32x16& o0, f32x16& o1, const u16* Vs, int dl,
;                  bool need_mask, int r, int h) {
;     ...
;     for (int i = 0; i < 16; ++i) {
;       const int ci = 32 * t + (i & 3) + 8 * (i >> 2);
;       float a = t ? s1[i] : s0[i];
;       float z = __builtin_amdgcn_fmed3f(a, -126.f, 126.f);
;       float e = ex2(-z);
;       float lb = -lg2(1.f + e);
;       float xi = lb - z;
;       if (need_mask) {
;         bool valid = (ci < dl);
;         xi = valid ? xi : 0.f;
;         lb = valid ? lb : -INFINITY;
;       }
;       x[16 * t + i] = xi;
;       if (t) s1[i] = lb; else s0[i] = lb;
;     }
;   float gs[8], pg[8], pr[8];
; #pragma unroll
;   for (int g = 0; g < 8; ++g) {
;     gs[g] = (x[4 * g] + x[4 * g + 1]) + (x[4 * g + 2] + x[4 * g + 3]);
;     pg[g] = shx(gs[g], r + 32 * h);
;     pr[g] = gs[g] + pg[g];
	v_cndmask_b32_e64 v68, 0, v65, s[2:3]
	v_med3_f32 v65, v78, s94, v198
	v_cndmask_b32_e64 v77, v199, -v69, s[2:3]
	v_exp_f32_e64 v69, -v65
	v_cmp_lt_i32_e64 s[2:3], 26, v0
	s_or_b64 s[2:3], s[42:43], s[2:3]
	v_add_f32_e32 v69, 1.0, v69
	v_log_f32_e32 v69, v69
	s_nop 0
	v_sub_f32_e64 v65, -v69, v65
	v_cndmask_b32_e64 v72, 0, v65, s[2:3]
	v_med3_f32 v65, v79, s94, v198
	v_cndmask_b32_e64 v78, v199, -v69, s[2:3]
	v_exp_f32_e64 v69, -v65
	v_cmp_lt_i32_e64 s[2:3], 27, v0
	s_or_b64 s[2:3], s[42:43], s[2:3]
	v_add_f32_e32 v69, 1.0, v69
	v_log_f32_e32 v69, v69
	s_nop 0
	v_sub_f32_e64 v65, -v69, v65
	v_cndmask_b32_e64 v74, 0, v65, s[2:3]
	v_exp_f32_e64 v65, -v48
	v_cndmask_b32_e64 v79, v199, -v69, s[2:3]
	v_cmp_lt_i32_e64 s[2:3], 32, v0
	s_or_b64 s[2:3], s[42:43], s[2:3]
	v_add_f32_e32 v65, 1.0, v65
	v_log_f32_e32 v65, v65
	s_nop 0
	v_sub_f32_e64 v48, -v65, v48
	v_cndmask_b32_e64 v69, 0, v48, s[2:3]
	v_med3_f32 v48, v49, s94, v198
	v_exp_f32_e64 v49, -v48
	v_cndmask_b32_e64 v167, v199, -v65, s[2:3]
	v_cmp_lt_i32_e64 s[2:3], 33, v0
	s_or_b64 s[2:3], s[42:43], s[2:3]
	v_add_f32_e32 v49, 1.0, v49
	v_log_f32_e32 v49, v49
	s_nop 0
	v_sub_f32_e64 v48, -v49, v48
	v_cndmask_b32_e64 v220, 0, v48, s[2:3]
	v_med3_f32 v48, v50, s94, v198
	v_cndmask_b32_e64 v219, v199, -v49, s[2:3]
	v_exp_f32_e64 v49, -v48
	v_cmp_lt_i32_e64 s[2:3], 34, v0
	s_or_b64 s[2:3], s[42:43], s[2:3]
	v_add_f32_e32 v49, 1.0, v49
	v_log_f32_e32 v49, v49
	s_nop 0
	v_sub_f32_e64 v48, -v49, v48
	v_cndmask_b32_e64 v222, 0, v48, s[2:3]
	v_med3_f32 v48, v51, s94, v198
	v_cndmask_b32_e64 v221, v199, -v49, s[2:3]
	v_exp_f32_e64 v49, -v48
	v_cmp_lt_i32_e64 s[2:3], 35, v0
	s_or_b64 s[2:3], s[42:43], s[2:3]
	v_add_f32_e32 v49, 1.0, v49
	v_log_f32_e32 v49, v49
	s_nop 0
	v_sub_f32_e64 v48, -v49, v48
	v_cndmask_b32_e64 v224, 0, v48, s[2:3]
	v_med3_f32 v48, v52, s94, v198
	v_cndmask_b32_e64 v223, v199, -v49, s[2:3]
	v_exp_f32_e64 v49, -v48
	v_cmp_lt_i32_e64 s[2:3], 40, v0
	s_or_b64 s[2:3], s[42:43], s[2:3]
	v_add_f32_e32 v49, 1.0, v49
	v_log_f32_e32 v49, v49
	s_nop 0
	v_sub_f32_e64 v48, -v49, v48
	v_cndmask_b32_e64 v51, 0, v48, s[2:3]
	v_med3_f32 v48, v53, s94, v198
	v_cndmask_b32_e64 v52, v199, -v49, s[2:3]
	v_exp_f32_e64 v49, -v48
	v_cmp_lt_i32_e64 s[2:3], 41, v0
	s_or_b64 s[2:3], s[42:43], s[2:3]
	v_add_f32_e32 v49, 1.0, v49
	v_log_f32_e32 v49, v49
	s_nop 0
	v_sub_f32_e64 v48, -v49, v48
	v_cndmask_b32_e64 v53, 0, v48, s[2:3]
	v_med3_f32 v48, v54, s94, v198
	v_cndmask_b32_e64 v75, v199, -v49, s[2:3]
	v_exp_f32_e64 v49, -v48
	v_cmp_lt_i32_e64 s[2:3], 42, v0
	s_or_b64 s[2:3], s[42:43], s[2:3]
	v_add_f32_e32 v49, 1.0, v49
	v_log_f32_e32 v49, v49
	s_nop 0
	v_sub_f32_e64 v48, -v49, v48
	v_cndmask_b32_e64 v225, 0, v48, s[2:3]
	v_med3_f32 v48, v55, s94, v198
	v_cndmask_b32_e64 v226, v199, -v49, s[2:3]
	v_exp_f32_e64 v49, -v48
	v_cmp_lt_i32_e64 s[2:3], 43, v0
	s_or_b64 s[2:3], s[42:43], s[2:3]
	v_add_f32_e32 v49, 1.0, v49
	v_log_f32_e32 v49, v49
	s_nop 0
	v_sub_f32_e64 v48, -v49, v48
	v_cndmask_b32_e64 v227, 0, v48, s[2:3]
	v_med3_f32 v48, v56, s94, v198
	v_cndmask_b32_e64 v228, v199, -v49, s[2:3]
	v_exp_f32_e64 v49, -v48
	v_cmp_lt_i32_e64 s[2:3], 48, v0
	s_or_b64 s[2:3], s[42:43], s[2:3]
	v_add_f32_e32 v49, 1.0, v49
	v_log_f32_e32 v49, v49
	s_nop 0
	v_sub_f32_e64 v48, -v49, v48
	v_cndmask_b32_e64 v56, v199, -v49, s[2:3]
	v_med3_f32 v49, v57, s94, v198
	v_exp_f32_e64 v50, -v49
	v_cndmask_b32_e64 v48, 0, v48, s[2:3]
	v_cmp_lt_i32_e64 s[2:3], 49, v0
	s_or_b64 s[2:3], s[42:43], s[2:3]
	v_add_f32_e32 v50, 1.0, v50
	v_log_f32_e32 v54, v50
	s_nop 0
	v_sub_f32_e64 v49, -v54, v49
	v_cndmask_b32_e64 v50, 0, v49, s[2:3]
	v_med3_f32 v49, v58, s94, v198
	v_cndmask_b32_e64 v57, v199, -v54, s[2:3]
	v_exp_f32_e64 v54, -v49
	v_cmp_lt_i32_e64 s[2:3], 50, v0
	s_or_b64 s[2:3], s[42:43], s[2:3]
	v_add_f32_e32 v54, 1.0, v54
	v_log_f32_e32 v54, v54
	s_nop 0
	v_sub_f32_e64 v49, -v54, v49
	v_cndmask_b32_e64 v58, 0, v49, s[2:3]
	v_med3_f32 v49, v59, s94, v198
	v_cndmask_b32_e64 v229, v199, -v54, s[2:3]
	v_exp_f32_e64 v54, -v49
	v_cmp_lt_i32_e64 s[2:3], 51, v0
	s_or_b64 s[2:3], s[42:43], s[2:3]
	v_add_f32_e32 v54, 1.0, v54
	v_log_f32_e32 v54, v54
	s_nop 0
	v_sub_f32_e64 v49, -v54, v49
	v_cndmask_b32_e64 v59, 0, v49, s[2:3]
	v_med3_f32 v49, v60, s94, v198
	v_cndmask_b32_e64 v230, v199, -v54, s[2:3]
	v_exp_f32_e64 v54, -v49
	v_cmp_lt_i32_e64 s[2:3], 56, v0
	s_or_b64 s[2:3], s[42:43], s[2:3]
	v_add_f32_e32 v54, 1.0, v54
	v_log_f32_e32 v54, v54
	s_nop 0
	v_sub_f32_e64 v49, -v54, v49
	v_cndmask_b32_e64 v60, v199, -v54, s[2:3]
	v_med3_f32 v54, v61, s94, v198
	v_exp_f32_e64 v55, -v54
	v_cndmask_b32_e64 v49, 0, v49, s[2:3]
	v_cmp_lt_i32_e64 s[2:3], 57, v0
	s_or_b64 s[2:3], s[42:43], s[2:3]
	v_add_f32_e32 v55, 1.0, v55
	v_log_f32_e32 v55, v55
	s_nop 0
	v_sub_f32_e64 v54, -v55, v54
	v_cndmask_b32_e64 v61, 0, v54, s[2:3]
	v_med3_f32 v54, v62, s94, v198
	v_cndmask_b32_e64 v231, v199, -v55, s[2:3]
	v_exp_f32_e64 v55, -v54
	v_cmp_lt_i32_e64 s[2:3], 58, v0
	s_or_b64 s[2:3], s[42:43], s[2:3]
	v_add_f32_e32 v49, v49, v61
	v_add_f32_e32 v55, 1.0, v55
	v_log_f32_e32 v55, v55
	s_nop 0
	v_sub_f32_e64 v54, -v55, v54
	v_cndmask_b32_e64 v62, 0, v54, s[2:3]
	v_med3_f32 v54, v63, s94, v198
	v_cndmask_b32_e64 v232, v199, -v55, s[2:3]
	v_exp_f32_e64 v55, -v54
	v_cmp_lt_i32_e64 s[2:3], 59, v0
	s_or_b64 s[2:3], s[42:43], s[2:3]
	v_add_f32_e32 v0, v15, v207
	v_add_f32_e32 v55, 1.0, v55
	v_log_f32_e32 v55, v55
	v_add_f32_e32 v15, v209, v211
	v_add_f32_e32 v15, v0, v15
	v_add_f32_e32 v0, v67, v214
	v_sub_f32_e64 v54, -v55, v54
	v_cndmask_b32_e64 v63, 0, v54, s[2:3]
	v_add_f32_e32 v54, v216, v218
	v_add_f32_e32 v0, v0, v54
	ds_bpermute_b32 v234, v180, v0
	v_add_f32_e32 v54, v222, v224
	v_cndmask_b32_e64 v233, v199, -v55, s[2:3]
	ds_bpermute_b32 v65, v180, v15
	s_mov_b32 s2, 0xc3200000
	s_waitcnt lgkmcnt(1)
; DI float ex2(float x) { return __builtin_amdgcn_exp2f(x); }
; DI f32x16 mfma(bf16x8 a, bf16x8 b, f32x16 c) { return __builtin_amdgcn_mfma_f32_32x32x16_bf16(a, b, c, 0, 0, 0); }
; DI void stick_pv(f32x16& s0, f32x16& s1, float& R, f32x16& o0, f32x16& o1, const u16* Vs, int dl,
;                  bool need_mask, int r, int h) {
;     ...
;   float gs[8], pg[8], pr[8];
; #pragma unroll
;   for (int g = 0; g < 8; ++g) {
;     gs[g] = (x[4 * g] + x[4 * g + 1]) + (x[4 * g + 2] + x[4 * g + 3]);
;     pg[g] = shx(gs[g], r + 32 * h);
;     pr[g] = gs[g] + pg[g];
;   }
;   float suf = 0.f;
; #pragma unroll
;   for (int g = 7; g >= 0; --g) {
;     float base = R + suf + (h == 0 ? pg[g] : 0.f);
;     float t3 = base, t2 = t3 + x[4 * g + 3], t1 = t2 + x[4 * g + 2], t0 = t1 + x[4 * g + 1];
;     const int i = 4 * (g & 3);
;     if (g >= 4) {
;       s1[i] = ex2(s1[i] + t0); s1[i + 1] = ex2(s1[i + 1] + t1); s1[i + 2] = ex2(s1[i + 2] + t2); s1[i + 3] = ex2(s1[i + 3] + t3);
;     } else {
;       s0[i] = ex2(s0[i] + t0); s0[i + 1] = ex2(s0[i + 1] + t1); s0[i + 2] = ex2(s0[i + 2] + t2); s0[i + 3] = ex2(s0[i + 3] + t3);
;     }
;     suf += pr[g];
;   }
;   R += suf;
; #pragma unroll
;   for (int kk = 0; kk < 4; ++kk) {
;     const int s = kk & 1;
;     unsigned u0, u1, u2, u3;
;     if (kk < 2) {
;       u0 = pk2(s0[8 * s], s0[8 * s + 1]); u1 = pk2(s0[8 * s + 2], s0[8 * s + 3]);
;       u2 = pk2(s0[8 * s + 4], s0[8 * s + 5]); u3 = pk2(s0[8 * s + 6], s0[8 * s + 7]);
;     } else {
;       u0 = pk2(s1[8 * s], s1[8 * s + 1]); u1 = pk2(s1[8 * s + 2], s1[8 * s + 3]);
;       u2 = pk2(s1[8 * s + 4], s1[8 * s + 5]); u3 = pk2(s1[8 * s + 6], s1[8 * s + 7]);
;     }
;     u32x4 uu = {u0, u1, u2, u3};
;     bf16x8 pf = __builtin_bit_cast(bf16x8, uu);
;     bf16x8 v0 = ldsv(Vs + r * LSTR + kk * 16 + 8 * h);
;     bf16x8 v1 = ldsv(Vs + (32 + r) * LSTR + kk * 16 + 8 * h);
;     o0 = mfma(v0, pf, o0);
;     o1 = mfma(v1, pf, o1);
;   }
; template <int MODE>
; DI void attn_item(const Params& p, int layer, int b, int head, int qblk, u16* sm, volatile LAS int* s_done_, int wv) {
;     ...
;               wdone = __all(R < -160.f) ? 1 : 0;
	v_add_f32_e32 v67, v0, v234
	v_add_f32_e32 v0, v69, v220
	v_add_f32_e32 v71, v0, v54
	v_add_f32_e32 v0, v51, v53
	v_add_f32_e32 v51, v225, v227
	v_add_f32_e32 v0, v0, v51
	v_add_f32_e32 v51, v62, v63
	v_add_f32_e32 v48, v48, v50
	v_add_f32_e32 v49, v49, v51
	ds_bpermute_b32 v55, v180, v49
	ds_bpermute_b32 v235, v180, v0
	v_add_f32_e32 v54, v58, v59
	ds_bpermute_b32 v69, v180, v71
	s_waitcnt lgkmcnt(3)
	v_add_f32_e32 v14, v14, v64
	v_add_f32_e32 v15, v15, v65
	s_waitcnt lgkmcnt(2)
	v_add_f32_e32 v48, v48, v54
	v_add_f32_e32 v49, v49, v55
	s_waitcnt lgkmcnt(1)
	v_add_f32_e32 v73, v0, v235
	ds_bpermute_b32 v0, v180, v48
	v_cndmask_b32_e32 v51, 0, v55, vcc
	v_add_f32_e32 v51, v236, v51
	v_add_f32_e32 v54, v63, v51
	v_add_f32_e32 v51, v233, v51
	s_waitcnt lgkmcnt(0)
	v_add_f32_e32 v48, v48, v0
	v_add_f32_e32 v49, v49, v1
	v_exp_f32_e32 v233, v51
	v_add_f32_e32 v51, v184, v49
	v_cndmask_b32_e32 v0, 0, v0, vcc
	v_add_f32_e32 v0, v0, v51
	v_add_f32_e32 v55, v62, v54
	v_add_f32_e32 v54, v232, v54
	v_add_f32_e32 v51, v59, v0
	v_exp_f32_e32 v232, v54
	v_add_f32_e32 v54, v58, v51
	v_add_f32_e32 v50, v50, v54
	v_add_f32_e32 v50, v56, v50
	v_exp_f32_e32 v237, v50
	v_add_f32_e32 v50, v57, v54
	v_exp_f32_e32 v238, v50
	v_add_f32_e32 v50, v229, v51
	v_pk_add_f32 v[48:49], v[48:49], v[48:49] op_sel:[0,1] op_sel_hi:[1,0]
	v_exp_f32_e32 v229, v50
	v_add_f32_e32 v49, v184, v48
	v_cndmask_b32_e32 v50, 0, v235, vcc
	v_add_f32_e32 v49, v50, v49
	v_add_f32_e32 v50, v227, v49
	v_add_f32_e32 v51, v225, v50
	v_add_f32_e32 v53, v53, v51
	v_add_f32_e32 v51, v75, v51
	v_add_f32_e32 v50, v226, v50
	v_add_f32_e32 v49, v228, v49
	v_mov_b32_e32 v75, v48
	v_exp_f32_e32 v227, v51
	v_exp_f32_e32 v226, v50
	v_exp_f32_e32 v228, v49
	v_add_f32_e32 v50, v70, v68
	v_add_f32_e32 v51, v71, v69
	v_add_f32_e32 v48, v72, v74
	v_add_f32_e32 v49, v73, v75
	v_add_f32_e32 v52, v52, v53
	v_add_f32_e32 v50, v50, v48
	v_add_f32_e32 v51, v51, v49
	ds_bpermute_b32 v48, v180, v50
	v_exp_f32_e32 v225, v52
	v_cndmask_b32_e32 v52, 0, v69, vcc
	v_add_f32_e32 v49, v184, v49
	v_add_f32_e32 v49, v52, v49
	v_add_f32_e32 v52, v224, v49
	v_add_f32_e32 v49, v223, v49
	s_waitcnt lgkmcnt(0)
	v_add_f32_e32 v50, v50, v48
	v_exp_f32_e32 v73, v49
	v_add_f32_e32 v49, v184, v51
	v_cndmask_b32_e32 v48, 0, v48, vcc
	v_add_f32_e32 v53, v222, v52
	v_add_f32_e32 v48, v48, v49
	v_add_f32_e32 v54, v220, v53
	v_add_f32_e32 v52, v221, v52
	v_add_f32_e32 v49, v74, v48
	v_add_f32_e32 v54, v167, v54
	v_exp_f32_e32 v71, v52
	v_add_f32_e32 v52, v72, v49
	v_add_f32_e32 v49, v78, v49
	v_add_f32_e32 v48, v79, v48
	v_add_f32_e32 v167, v50, v51
	v_exp_f32_e32 v74, v49
	v_exp_f32_e32 v75, v48
	v_add_f32_e32 v48, v184, v167
	v_cndmask_b32_e32 v49, 0, v234, vcc
	v_add_f32_e32 v48, v49, v48
	v_add_f32_e32 v49, v218, v48
	v_add_f32_e32 v50, v216, v49
	v_add_f32_e32 v49, v215, v49
	v_add_f32_e32 v48, v217, v48
	v_exp_f32_e32 v78, v49
	v_exp_f32_e32 v79, v48
	v_add_f32_e32 v48, v66, v166
	v_add_f32_e32 v49, v67, v167
	v_add_f32_e32 v53, v219, v53
	v_add_f32_e32 v51, v214, v50
	v_add_f32_e32 v50, v213, v50
	v_add_f32_e32 v14, v14, v48
	v_add_f32_e32 v15, v15, v49
	v_exp_f32_e32 v70, v53
	v_add_f32_e32 v53, v68, v52
	v_add_f32_e32 v52, v77, v52
	v_exp_f32_e32 v77, v50
	v_cndmask_b32_e32 v50, 0, v65, vcc
	ds_bpermute_b32 v48, v180, v14
	v_add_f32_e32 v49, v184, v49
	v_add_f32_e32 v49, v50, v49
	v_add_f32_e32 v51, v212, v51
	v_add_f32_e32 v50, v211, v49
	v_add_f32_e32 v53, v76, v53
	v_exp_f32_e32 v76, v51
	v_add_f32_e32 v51, v209, v50
	v_exp_f32_e32 v72, v52
	v_add_f32_e32 v52, v207, v51
	v_add_f32_e32 v51, v206, v51
	v_exp_f32_e32 v68, v53
	s_waitcnt lgkmcnt(0)
	v_add_f32_e32 v14, v14, v48
	v_exp_f32_e32 v53, v51
	v_add_f32_e32 v51, v184, v15
	v_cndmask_b32_e32 v48, 0, v48, vcc
	v_add_f32_e32 v48, v48, v51
	v_add_f32_e32 v51, v166, v48
	v_add_f32_e32 v61, v61, v55
	v_add_f32_e32 v55, v231, v55
	v_exp_f32_e32 v69, v54
	v_add_f32_e32 v54, v66, v51
	v_exp_f32_e32 v231, v55
	v_add_f32_e32 v55, v64, v54
	v_add_f32_e32 v52, v205, v52
	v_add_f32_e32 v50, v208, v50
	v_add_f32_e32 v49, v210, v49
	v_add_f32_e32 v55, v165, v55
	v_add_f32_e32 v54, v185, v54
	v_add_f32_e32 v51, v186, v51
	v_add_f32_e32 v48, v204, v48
	v_exp_f32_e32 v52, v52
	v_exp_f32_e32 v50, v50
	v_exp_f32_e32 v49, v49
	v_exp_f32_e32 v55, v55
	v_exp_f32_e32 v54, v54
	v_exp_f32_e32 v56, v51
	v_exp_f32_e32 v48, v48
	v_add_f32_e32 v60, v60, v61
	v_exp_f32_e32 v236, v60
	v_cvt_pk_bf16_f32 v51, v50, v49
	v_cvt_pk_bf16_f32 v50, v52, v53
	v_cvt_pk_bf16_f32 v49, v56, v48
	v_cvt_pk_bf16_f32 v48, v55, v54
	ds_read_b128 v[52:55], v155 offset:32256
	ds_read_b128 v[56:59], v155 offset:27648
	ds_read_b128 v[60:63], v155 offset:27680
	s_waitcnt lgkmcnt(2)
	v_mfma_f32_32x32x16_bf16 v[16:31], v[52:55], v[48:51], v[16:31]
	ds_read_b128 v[52:55], v155 offset:32288
	v_add_f32_e32 v0, v230, v0
	v_exp_f32_e32 v0, v0
	v_add_f32_e32 v14, v14, v15
	v_add_f32_e32 v184, v184, v14
	v_cmp_gt_f32_e64 s[2:3], s2, v184
	s_cmp_eq_u64 s[2:3], exec
	s_waitcnt lgkmcnt(2)
	v_mfma_f32_32x32x16_bf16 v[32:47], v[56:59], v[48:51], v[32:47]
	v_cvt_pk_bf16_f32 v51, v74, v75
	v_cvt_pk_bf16_f32 v50, v68, v72
	v_cvt_pk_bf16_f32 v49, v78, v79
	v_cvt_pk_bf16_f32 v48, v76, v77
	s_cselect_b64 s[2:3], -1, 0
	v_cndmask_b32_e64 v64, 0, 1, s[2:3]
	s_waitcnt lgkmcnt(1)
	v_mfma_f32_32x32x16_bf16 v[32:47], v[60:63], v[48:51], v[32:47]
	s_waitcnt lgkmcnt(0)
	v_mfma_f32_32x32x16_bf16 v[16:31], v[52:55], v[48:51], v[16:31]
	ds_read_b128 v[52:55], v155 offset:27712
	ds_read_b128 v[56:59], v155 offset:32320
	v_cvt_pk_bf16_f32 v51, v226, v228
	v_cvt_pk_bf16_f32 v50, v225, v227
	v_cvt_pk_bf16_f32 v49, v71, v73
	v_cvt_pk_bf16_f32 v48, v69, v70
	s_waitcnt lgkmcnt(1)
	s_nop 0
	v_mfma_f32_32x32x16_bf16 v[32:47], v[52:55], v[48:51], v[32:47]
	s_waitcnt lgkmcnt(0)
	v_mfma_f32_32x32x16_bf16 v[16:31], v[56:59], v[48:51], v[16:31]
	ds_read_b128 v[52:55], v155 offset:27744
	ds_read_b128 v[56:59], v155 offset:32352
	v_cvt_pk_bf16_f32 v51, v232, v233
	v_cvt_pk_bf16_f32 v50, v236, v231
	v_cvt_pk_bf16_f32 v49, v229, v0
	v_cvt_pk_bf16_f32 v48, v237, v238
	s_waitcnt lgkmcnt(1)
	s_nop 0
	v_mfma_f32_32x32x16_bf16 v[32:47], v[52:55], v[48:51], v[32:47]
	s_waitcnt lgkmcnt(0)
	v_mfma_f32_32x32x16_bf16 v[16:31], v[56:59], v[48:51], v[16:31]

; DI float ex2(float x) { return __builtin_amdgcn_exp2f(x); }
; DI float lg2(float x) { return __builtin_amdgcn_logf(x); }
; DI f32x16 mfma(bf16x8 a, bf16x8 b, f32x16 c) { return __builtin_amdgcn_mfma_f32_32x32x16_bf16(a, b, c, 0, 0, 0); }
; DI void stick_pv(f32x16& s0, f32x16& s1, float& R, f32x16& o0, f32x16& o1, const u16* Vs, int dl,
;                  bool need_mask, int r, int h) {
;   float x[32];
; #pragma unroll
;   for (int t = 0; t < 2; ++t)
; #pragma unroll
;     for (int i = 0; i < 16; ++i) {
;       const int ci = 32 * t + (i & 3) + 8 * (i >> 2);
;       float a = t ? s1[i] : s0[i];
;       float z = __builtin_amdgcn_fmed3f(a, -126.f, 126.f);
;       float e = ex2(-z);
;       float lb = -lg2(1.f + e);
;       float xi = lb - z;
;       if (need_mask) {
;         bool valid = (ci < dl);
;         xi = valid ? xi : 0.f;
;         lb = valid ? lb : -INFINITY;
;       }
;       x[16 * t + i] = xi;
;       if (t) s1[i] = lb; else s0[i] = lb;
;     }
; template <int MODE>
; DI void attn_item(const Params& p, int layer, int b, int head, int qblk, u16* sm, volatile LAS int* s_done_, int wv) {
;     ...
;               f32x16 sa[2];
; #pragma unroll
;               for (int e = 0; e < 16; ++e) { sa[0][e] = 0.f; sa[1][e] = 0.f; }
; #pragma unroll
;               for (int t = 0; t < 2; ++t)
; #pragma unroll
;                 for (int ks = 0; ks < 4; ++ks) {
;                   bf16x8 kf = ldsv(Kc + (32 * t + r) * LSTR + ks * 16 + 8 * h);
;                   sa[t] = mfma(kf, qf[ks], sa[t]);
;                 }
;               stick_pv(sa[0], sa[1], R, o[0], o[1], Vc, dl, need_mask, r, h);
.LBB0_239:
	s_xor_b32 s2, s87, 0x3fffffc
	v_add_lshl_u32 v0, s2, v173, 6
	v_cmp_lt_i32_e64 s[2:3], v0, v176
	v_cmp_eq_u32_e64 s[38:39], 0, v64
	s_and_b64 s[2:3], s[2:3], s[38:39]
	s_and_saveexec_b64 s[18:19], s[2:3]
	s_cbranch_execz .LBB0_241
	v_or_b32_e32 v14, 63, v0
	v_cmp_lt_i32_e64 s[38:39], v14, v148
	v_add_u32_e32 v14, v152, v181
	s_waitcnt vmcnt(3)
	s_waitcnt vmcnt(2)
	ds_read_b128 v[48:51], v14 offset:55296
	ds_read_b128 v[52:55], v14 offset:55328
	ds_read_b128 v[240:243], v14 offset:55360
	ds_read_b128 v[244:247], v14 offset:55392
	ds_read_b128 v[204:207], v14 offset:59936
	v_or_b32_e32 v0, v0, v177
	s_waitcnt lgkmcnt(4)
	v_mfma_f32_32x32x16_bf16 v[64:79], v[48:51], v[88:91], 0
	v_sub_u32_e32 v0, v149, v0
	v_cmp_lt_i32_e64 s[2:3], 0, v0
	s_or_b64 s[2:3], s[38:39], s[2:3]
	v_add_f32_e32 v236, 0, v184
	s_waitcnt lgkmcnt(3)
	v_mfma_f32_32x32x16_bf16 v[64:79], v[52:55], v[80:83], v[64:79]
	s_waitcnt lgkmcnt(2)
	v_mfma_f32_32x32x16_bf16 v[64:79], v[240:243], v[84:87], v[64:79]
	ds_read_b128 v[240:243], v14 offset:59904
	s_waitcnt lgkmcnt(2)
	v_mfma_f32_32x32x16_bf16 v[64:79], v[244:247], v[92:95], v[64:79]
	ds_read_b128 v[244:247], v14 offset:59968
	s_waitcnt vmcnt(0) lgkmcnt(1)
	v_mfma_f32_32x32x16_bf16 v[48:63], v[240:243], v[88:91], 0
	ds_read_b128 v[240:243], v14 offset:60000
	v_mfma_f32_32x32x16_bf16 v[48:63], v[204:207], v[80:83], v[48:63]
	s_waitcnt lgkmcnt(1)
	v_mfma_f32_32x32x16_bf16 v[48:63], v[244:247], v[84:87], v[48:63]
	s_nop 3
	v_med3_f32 v14, v64, s94, v198
	v_exp_f32_e64 v15, -v14
	s_nop 0
	v_add_f32_e32 v15, 1.0, v15
	v_log_f32_e32 v15, v15
	s_waitcnt lgkmcnt(0)
	v_mfma_f32_32x32x16_bf16 v[48:63], v[240:243], v[92:95], v[48:63]
	v_sub_f32_e64 v14, -v15, v14
	v_cndmask_b32_e64 v165, v199, -v15, s[2:3]
	v_med3_f32 v15, v65, s94, v198
	v_exp_f32_e64 v64, -v15
	v_cndmask_b32_e64 v14, 0, v14, s[2:3]
	v_cmp_lt_i32_e64 s[2:3], 1, v0
	s_or_b64 s[2:3], s[38:39], s[2:3]
	v_add_f32_e32 v64, 1.0, v64
	v_log_f32_e32 v65, v64
	s_nop 2
	v_med3_f32 v48, v48, s94, v198
	v_sub_f32_e64 v15, -v65, v15
	v_cndmask_b32_e64 v64, 0, v15, s[2:3]
	v_med3_f32 v15, v66, s94, v198
	v_cndmask_b32_e64 v185, v199, -v65, s[2:3]
	v_exp_f32_e64 v65, -v15
	v_cmp_lt_i32_e64 s[2:3], 2, v0
	s_or_b64 s[2:3], s[38:39], s[2:3]
	v_add_f32_e32 v65, 1.0, v65
	v_log_f32_e32 v65, v65
	s_nop 0
	v_sub_f32_e64 v15, -v65, v15
	v_cndmask_b32_e64 v66, 0, v15, s[2:3]
	v_med3_f32 v15, v67, s94, v198
	v_cndmask_b32_e64 v186, v199, -v65, s[2:3]
	v_exp_f32_e64 v65, -v15
	v_cmp_lt_i32_e64 s[2:3], 3, v0
	s_or_b64 s[2:3], s[38:39], s[2:3]
	v_add_f32_e32 v65, 1.0, v65
	v_log_f32_e32 v65, v65
	s_nop 0
	v_sub_f32_e64 v15, -v65, v15
	v_cndmask_b32_e64 v166, 0, v15, s[2:3]
	v_med3_f32 v15, v68, s94, v198
	v_cndmask_b32_e64 v204, v199, -v65, s[2:3]
	v_exp_f32_e64 v65, -v15
	v_cmp_lt_i32_e64 s[2:3], 8, v0
	s_or_b64 s[2:3], s[38:39], s[2:3]
	v_add_f32_e32 v65, 1.0, v65
	v_log_f32_e32 v65, v65
	s_nop 0
	v_sub_f32_e64 v15, -v65, v15
	v_cndmask_b32_e64 v205, v199, -v65, s[2:3]
	v_med3_f32 v65, v69, s94, v198
	v_exp_f32_e64 v67, -v65
	v_cndmask_b32_e64 v15, 0, v15, s[2:3]
	v_cmp_lt_i32_e64 s[2:3], 9, v0
	s_or_b64 s[2:3], s[38:39], s[2:3]
	v_add_f32_e32 v67, 1.0, v67
	v_log_f32_e32 v67, v67
	s_nop 0
	v_sub_f32_e64 v65, -v67, v65
	v_cndmask_b32_e64 v207, 0, v65, s[2:3]
	v_med3_f32 v65, v70, s94, v198
	v_cndmask_b32_e64 v206, v199, -v67, s[2:3]
	v_exp_f32_e64 v67, -v65
	v_cmp_lt_i32_e64 s[2:3], 10, v0
	s_or_b64 s[2:3], s[38:39], s[2:3]
	v_add_f32_e32 v67, 1.0, v67
	v_log_f32_e32 v67, v67
	s_nop 0
	v_sub_f32_e64 v65, -v67, v65
	v_cndmask_b32_e64 v209, 0, v65, s[2:3]
	v_med3_f32 v65, v71, s94, v198
	v_cndmask_b32_e64 v208, v199, -v67, s[2:3]
	v_exp_f32_e64 v67, -v65
	v_cmp_lt_i32_e64 s[2:3], 11, v0
	s_or_b64 s[2:3], s[38:39], s[2:3]
	v_add_f32_e32 v67, 1.0, v67
	v_log_f32_e32 v67, v67
	s_nop 0
	v_sub_f32_e64 v65, -v67, v65
	v_cndmask_b32_e64 v211, 0, v65, s[2:3]
	v_med3_f32 v65, v72, s94, v198
	v_cndmask_b32_e64 v210, v199, -v67, s[2:3]
	v_exp_f32_e64 v67, -v65
	v_cmp_lt_i32_e64 s[2:3], 16, v0
	s_or_b64 s[2:3], s[38:39], s[2:3]
	v_add_f32_e32 v67, 1.0, v67
	v_log_f32_e32 v68, v67
	s_nop 0
	v_sub_f32_e64 v65, -v68, v65
	v_cndmask_b32_e64 v67, 0, v65, s[2:3]
	v_med3_f32 v65, v73, s94, v198
	v_cndmask_b32_e64 v212, v199, -v68, s[2:3]
	v_exp_f32_e64 v68, -v65
	v_cmp_lt_i32_e64 s[2:3], 17, v0
	s_or_b64 s[2:3], s[38:39], s[2:3]
	v_add_f32_e32 v68, 1.0, v68
	v_log_f32_e32 v68, v68
	s_nop 0
	v_sub_f32_e64 v65, -v68, v65
	v_cndmask_b32_e64 v214, 0, v65, s[2:3]
	v_med3_f32 v65, v74, s94, v198
	v_cndmask_b32_e64 v213, v199, -v68, s[2:3]
	v_exp_f32_e64 v68, -v65
	v_cmp_lt_i32_e64 s[2:3], 18, v0
	s_or_b64 s[2:3], s[38:39], s[2:3]
	v_add_f32_e32 v68, 1.0, v68
	v_log_f32_e32 v68, v68
	s_nop 0
	v_sub_f32_e64 v65, -v68, v65
	v_cndmask_b32_e64 v216, 0, v65, s[2:3]
	v_med3_f32 v65, v75, s94, v198
	v_cndmask_b32_e64 v215, v199, -v68, s[2:3]
	v_exp_f32_e64 v68, -v65
	v_cmp_lt_i32_e64 s[2:3], 19, v0
	s_or_b64 s[2:3], s[38:39], s[2:3]
	v_add_f32_e32 v68, 1.0, v68
	v_log_f32_e32 v68, v68
	s_nop 0
	v_sub_f32_e64 v65, -v68, v65
	v_cndmask_b32_e64 v218, 0, v65, s[2:3]
	v_med3_f32 v65, v76, s94, v198
	v_cndmask_b32_e64 v217, v199, -v68, s[2:3]
	v_exp_f32_e64 v68, -v65
	v_cmp_lt_i32_e64 s[2:3], 24, v0
	s_or_b64 s[2:3], s[38:39], s[2:3]
	v_add_f32_e32 v68, 1.0, v68
	v_log_f32_e32 v68, v68
	s_nop 0
	v_sub_f32_e64 v65, -v68, v65
	v_cndmask_b32_e64 v70, 0, v65, s[2:3]
	v_med3_f32 v65, v77, s94, v198
	v_cndmask_b32_e64 v76, v199, -v68, s[2:3]
	v_exp_f32_e64 v68, -v65
	v_cmp_lt_i32_e64 s[2:3], 25, v0
	s_or_b64 s[2:3], s[38:39], s[2:3]
	v_add_f32_e32 v68, 1.0, v68
	v_log_f32_e32 v69, v68
	s_nop 0
	v_sub_f32_e64 v65, -v69, v65
; DI float ex2(float x) { return __builtin_amdgcn_exp2f(x); }
; DI float lg2(float x) { return __builtin_amdgcn_logf(x); }
; DI void stick_pv(f32x16& s0, f32x16& s1, float& R, f32x16& o0, f32x16& o1, const u16* Vs, int dl,
;                  bool need_mask, int r, int h) {
;     ...
;     for (int i = 0; i < 16; ++i) {
;       const int ci = 32 * t + (i & 3) + 8 * (i >> 2);
;       float a = t ? s1[i] : s0[i];
;       float z = __builtin_amdgcn_fmed3f(a, -126.f, 126.f);
;       float e = ex2(-z);
;       float lb = -lg2(1.f + e);
;       float xi = lb - z;
;       if (need_mask) {
;         bool valid = (ci < dl);
;         xi = valid ? xi : 0.f;
;         lb = valid ? lb : -INFINITY;
;       }
;       x[16 * t + i] = xi;
;       if (t) s1[i] = lb; else s0[i] = lb;
;     }
;   float gs[8], pg[8], pr[8];
; #pragma unroll
;   for (int g = 0; g < 8; ++g) {
;     gs[g] = (x[4 * g] + x[4 * g + 1]) + (x[4 * g + 2] + x[4 * g + 3]);
;     pg[g] = shx(gs[g], r + 32 * h);
;     pr[g] = gs[g] + pg[g];
	v_cndmask_b32_e64 v68, 0, v65, s[2:3]
	v_med3_f32 v65, v78, s94, v198
	v_cndmask_b32_e64 v77, v199, -v69, s[2:3]
	v_exp_f32_e64 v69, -v65
	v_cmp_lt_i32_e64 s[2:3], 26, v0
	s_or_b64 s[2:3], s[38:39], s[2:3]
	v_add_f32_e32 v69, 1.0, v69
	v_log_f32_e32 v69, v69
	s_nop 0
	v_sub_f32_e64 v65, -v69, v65
	v_cndmask_b32_e64 v72, 0, v65, s[2:3]
	v_med3_f32 v65, v79, s94, v198
	v_cndmask_b32_e64 v78, v199, -v69, s[2:3]
	v_exp_f32_e64 v69, -v65
	v_cmp_lt_i32_e64 s[2:3], 27, v0
	s_or_b64 s[2:3], s[38:39], s[2:3]
	v_add_f32_e32 v69, 1.0, v69
	v_log_f32_e32 v69, v69
	s_nop 0
	v_sub_f32_e64 v65, -v69, v65
	v_cndmask_b32_e64 v74, 0, v65, s[2:3]
	v_exp_f32_e64 v65, -v48
	v_cndmask_b32_e64 v79, v199, -v69, s[2:3]
	v_cmp_lt_i32_e64 s[2:3], 32, v0
	s_or_b64 s[2:3], s[38:39], s[2:3]
	v_add_f32_e32 v65, 1.0, v65
	v_log_f32_e32 v65, v65
	s_nop 0
	v_sub_f32_e64 v48, -v65, v48
	v_cndmask_b32_e64 v69, 0, v48, s[2:3]
	v_med3_f32 v48, v49, s94, v198
	v_exp_f32_e64 v49, -v48
	v_cndmask_b32_e64 v167, v199, -v65, s[2:3]
	v_cmp_lt_i32_e64 s[2:3], 33, v0
	s_or_b64 s[2:3], s[38:39], s[2:3]
	v_add_f32_e32 v49, 1.0, v49
	v_log_f32_e32 v49, v49
	s_nop 0
	v_sub_f32_e64 v48, -v49, v48
	v_cndmask_b32_e64 v220, 0, v48, s[2:3]
	v_med3_f32 v48, v50, s94, v198
	v_cndmask_b32_e64 v219, v199, -v49, s[2:3]
	v_exp_f32_e64 v49, -v48
	v_cmp_lt_i32_e64 s[2:3], 34, v0
	s_or_b64 s[2:3], s[38:39], s[2:3]
	v_add_f32_e32 v49, 1.0, v49
	v_log_f32_e32 v49, v49
	s_nop 0
	v_sub_f32_e64 v48, -v49, v48
	v_cndmask_b32_e64 v222, 0, v48, s[2:3]
	v_med3_f32 v48, v51, s94, v198
	v_cndmask_b32_e64 v221, v199, -v49, s[2:3]
	v_exp_f32_e64 v49, -v48
	v_cmp_lt_i32_e64 s[2:3], 35, v0
	s_or_b64 s[2:3], s[38:39], s[2:3]
	v_add_f32_e32 v49, 1.0, v49
	v_log_f32_e32 v49, v49
	s_nop 0
	v_sub_f32_e64 v48, -v49, v48
	v_cndmask_b32_e64 v224, 0, v48, s[2:3]
	v_med3_f32 v48, v52, s94, v198
	v_cndmask_b32_e64 v223, v199, -v49, s[2:3]
	v_exp_f32_e64 v49, -v48
	v_cmp_lt_i32_e64 s[2:3], 40, v0
	s_or_b64 s[2:3], s[38:39], s[2:3]
	v_add_f32_e32 v49, 1.0, v49
	v_log_f32_e32 v49, v49
	s_nop 0
	v_sub_f32_e64 v48, -v49, v48
	v_cndmask_b32_e64 v51, 0, v48, s[2:3]
	v_med3_f32 v48, v53, s94, v198
	v_cndmask_b32_e64 v52, v199, -v49, s[2:3]
	v_exp_f32_e64 v49, -v48
	v_cmp_lt_i32_e64 s[2:3], 41, v0
	s_or_b64 s[2:3], s[38:39], s[2:3]
	v_add_f32_e32 v49, 1.0, v49
	v_log_f32_e32 v49, v49
	s_nop 0
	v_sub_f32_e64 v48, -v49, v48
	v_cndmask_b32_e64 v53, 0, v48, s[2:3]
	v_med3_f32 v48, v54, s94, v198
	v_cndmask_b32_e64 v75, v199, -v49, s[2:3]
	v_exp_f32_e64 v49, -v48
	v_cmp_lt_i32_e64 s[2:3], 42, v0
	s_or_b64 s[2:3], s[38:39], s[2:3]
	v_add_f32_e32 v49, 1.0, v49
	v_log_f32_e32 v49, v49
	s_nop 0
	v_sub_f32_e64 v48, -v49, v48
	v_cndmask_b32_e64 v225, 0, v48, s[2:3]
	v_med3_f32 v48, v55, s94, v198
	v_cndmask_b32_e64 v226, v199, -v49, s[2:3]
	v_exp_f32_e64 v49, -v48
	v_cmp_lt_i32_e64 s[2:3], 43, v0
	s_or_b64 s[2:3], s[38:39], s[2:3]
	v_add_f32_e32 v49, 1.0, v49
	v_log_f32_e32 v49, v49
	s_nop 0
	v_sub_f32_e64 v48, -v49, v48
	v_cndmask_b32_e64 v227, 0, v48, s[2:3]
	v_med3_f32 v48, v56, s94, v198
	v_cndmask_b32_e64 v228, v199, -v49, s[2:3]
	v_exp_f32_e64 v49, -v48
	v_cmp_lt_i32_e64 s[2:3], 48, v0
	s_or_b64 s[2:3], s[38:39], s[2:3]
	v_add_f32_e32 v49, 1.0, v49
	v_log_f32_e32 v49, v49
	s_nop 0
	v_sub_f32_e64 v48, -v49, v48
	v_cndmask_b32_e64 v56, v199, -v49, s[2:3]
	v_med3_f32 v49, v57, s94, v198
	v_exp_f32_e64 v50, -v49
	v_cndmask_b32_e64 v48, 0, v48, s[2:3]
	v_cmp_lt_i32_e64 s[2:3], 49, v0
	s_or_b64 s[2:3], s[38:39], s[2:3]
	v_add_f32_e32 v50, 1.0, v50
	v_log_f32_e32 v54, v50
	s_nop 0
	v_sub_f32_e64 v49, -v54, v49
	v_cndmask_b32_e64 v50, 0, v49, s[2:3]
	v_med3_f32 v49, v58, s94, v198
	v_cndmask_b32_e64 v57, v199, -v54, s[2:3]
	v_exp_f32_e64 v54, -v49
	v_cmp_lt_i32_e64 s[2:3], 50, v0
	s_or_b64 s[2:3], s[38:39], s[2:3]
	v_add_f32_e32 v54, 1.0, v54
	v_log_f32_e32 v54, v54
	s_nop 0
	v_sub_f32_e64 v49, -v54, v49
	v_cndmask_b32_e64 v58, 0, v49, s[2:3]
	v_med3_f32 v49, v59, s94, v198
	v_cndmask_b32_e64 v229, v199, -v54, s[2:3]
	v_exp_f32_e64 v54, -v49
	v_cmp_lt_i32_e64 s[2:3], 51, v0
	s_or_b64 s[2:3], s[38:39], s[2:3]
	v_add_f32_e32 v54, 1.0, v54
	v_log_f32_e32 v54, v54
	s_nop 0
	v_sub_f32_e64 v49, -v54, v49
	v_cndmask_b32_e64 v59, 0, v49, s[2:3]
	v_med3_f32 v49, v60, s94, v198
	v_cndmask_b32_e64 v230, v199, -v54, s[2:3]
	v_exp_f32_e64 v54, -v49
	v_cmp_lt_i32_e64 s[2:3], 56, v0
	s_or_b64 s[2:3], s[38:39], s[2:3]
	v_add_f32_e32 v54, 1.0, v54
	v_log_f32_e32 v54, v54
	s_nop 0
	v_sub_f32_e64 v49, -v54, v49
	v_cndmask_b32_e64 v60, v199, -v54, s[2:3]
	v_med3_f32 v54, v61, s94, v198
	v_exp_f32_e64 v55, -v54
	v_cndmask_b32_e64 v49, 0, v49, s[2:3]
	v_cmp_lt_i32_e64 s[2:3], 57, v0
	s_or_b64 s[2:3], s[38:39], s[2:3]
	v_add_f32_e32 v55, 1.0, v55
	v_log_f32_e32 v55, v55
	s_nop 0
	v_sub_f32_e64 v54, -v55, v54
	v_cndmask_b32_e64 v61, 0, v54, s[2:3]
	v_med3_f32 v54, v62, s94, v198
	v_cndmask_b32_e64 v231, v199, -v55, s[2:3]
	v_exp_f32_e64 v55, -v54
	v_cmp_lt_i32_e64 s[2:3], 58, v0
	s_or_b64 s[2:3], s[38:39], s[2:3]
	v_add_f32_e32 v49, v49, v61
	v_add_f32_e32 v55, 1.0, v55
	v_log_f32_e32 v55, v55
	s_nop 0
	v_sub_f32_e64 v54, -v55, v54
	v_cndmask_b32_e64 v62, 0, v54, s[2:3]
	v_med3_f32 v54, v63, s94, v198
	v_cndmask_b32_e64 v232, v199, -v55, s[2:3]
	v_exp_f32_e64 v55, -v54
	v_cmp_lt_i32_e64 s[2:3], 59, v0
	s_or_b64 s[2:3], s[38:39], s[2:3]
	v_add_f32_e32 v0, v15, v207
	v_add_f32_e32 v55, 1.0, v55
	v_log_f32_e32 v55, v55
	v_add_f32_e32 v15, v209, v211
	v_add_f32_e32 v15, v0, v15
	v_add_f32_e32 v0, v67, v214
	v_sub_f32_e64 v54, -v55, v54
	v_cndmask_b32_e64 v63, 0, v54, s[2:3]
	v_add_f32_e32 v54, v216, v218
	v_add_f32_e32 v0, v0, v54
	ds_bpermute_b32 v234, v180, v0
	v_add_f32_e32 v54, v222, v224
	v_cndmask_b32_e64 v233, v199, -v55, s[2:3]
	ds_bpermute_b32 v65, v180, v15
	s_mov_b32 s2, 0xc3200000
	s_waitcnt lgkmcnt(1)
; DI float ex2(float x) { return __builtin_amdgcn_exp2f(x); }
; DI f32x16 mfma(bf16x8 a, bf16x8 b, f32x16 c) { return __builtin_amdgcn_mfma_f32_32x32x16_bf16(a, b, c, 0, 0, 0); }
; DI void stick_pv(f32x16& s0, f32x16& s1, float& R, f32x16& o0, f32x16& o1, const u16* Vs, int dl,
;                  bool need_mask, int r, int h) {
;     ...
;   float gs[8], pg[8], pr[8];
; #pragma unroll
;   for (int g = 0; g < 8; ++g) {
;     gs[g] = (x[4 * g] + x[4 * g + 1]) + (x[4 * g + 2] + x[4 * g + 3]);
;     pg[g] = shx(gs[g], r + 32 * h);
;     pr[g] = gs[g] + pg[g];
;   }
;   float suf = 0.f;
; #pragma unroll
;   for (int g = 7; g >= 0; --g) {
;     float base = R + suf + (h == 0 ? pg[g] : 0.f);
;     float t3 = base, t2 = t3 + x[4 * g + 3], t1 = t2 + x[4 * g + 2], t0 = t1 + x[4 * g + 1];
;     const int i = 4 * (g & 3);
;     if (g >= 4) {
;       s1[i] = ex2(s1[i] + t0); s1[i + 1] = ex2(s1[i + 1] + t1); s1[i + 2] = ex2(s1[i + 2] + t2); s1[i + 3] = ex2(s1[i + 3] + t3);
;     } else {
;       s0[i] = ex2(s0[i] + t0); s0[i + 1] = ex2(s0[i + 1] + t1); s0[i + 2] = ex2(s0[i + 2] + t2); s0[i + 3] = ex2(s0[i + 3] + t3);
;     }
;     suf += pr[g];
;   }
;   R += suf;
; #pragma unroll
;   for (int kk = 0; kk < 4; ++kk) {
;     const int s = kk & 1;
;     unsigned u0, u1, u2, u3;
;     if (kk < 2) {
;       u0 = pk2(s0[8 * s], s0[8 * s + 1]); u1 = pk2(s0[8 * s + 2], s0[8 * s + 3]);
;       u2 = pk2(s0[8 * s + 4], s0[8 * s + 5]); u3 = pk2(s0[8 * s + 6], s0[8 * s + 7]);
;     } else {
;       u0 = pk2(s1[8 * s], s1[8 * s + 1]); u1 = pk2(s1[8 * s + 2], s1[8 * s + 3]);
;       u2 = pk2(s1[8 * s + 4], s1[8 * s + 5]); u3 = pk2(s1[8 * s + 6], s1[8 * s + 7]);
;     }
;     u32x4 uu = {u0, u1, u2, u3};
;     bf16x8 pf = __builtin_bit_cast(bf16x8, uu);
;     bf16x8 v0 = ldsv(Vs + r * LSTR + kk * 16 + 8 * h);
;     bf16x8 v1 = ldsv(Vs + (32 + r) * LSTR + kk * 16 + 8 * h);
;     o0 = mfma(v0, pf, o0);
;     o1 = mfma(v1, pf, o1);
;   }
; template <int MODE>
; DI void attn_item(const Params& p, int layer, int b, int head, int qblk, u16* sm, volatile LAS int* s_done_, int wv) {
;     ...
;               wdone = __all(R < -160.f) ? 1 : 0;
	v_add_f32_e32 v67, v0, v234
	v_add_f32_e32 v0, v69, v220
	v_add_f32_e32 v71, v0, v54
	v_add_f32_e32 v0, v51, v53
	v_add_f32_e32 v51, v225, v227
	v_add_f32_e32 v0, v0, v51
	v_add_f32_e32 v51, v62, v63
	v_add_f32_e32 v48, v48, v50
	v_add_f32_e32 v49, v49, v51
	ds_bpermute_b32 v55, v180, v49
	ds_bpermute_b32 v235, v180, v0
	v_add_f32_e32 v54, v58, v59
	ds_bpermute_b32 v69, v180, v71
	s_waitcnt lgkmcnt(3)
	v_add_f32_e32 v14, v14, v64
	v_add_f32_e32 v15, v15, v65
	s_waitcnt lgkmcnt(2)
	v_add_f32_e32 v48, v48, v54
	v_add_f32_e32 v49, v49, v55
	s_waitcnt lgkmcnt(1)
	v_add_f32_e32 v73, v0, v235
	ds_bpermute_b32 v0, v180, v48
	v_cndmask_b32_e32 v51, 0, v55, vcc
	v_add_f32_e32 v51, v236, v51
	v_add_f32_e32 v54, v63, v51
	v_add_f32_e32 v51, v233, v51
	s_waitcnt lgkmcnt(0)
	v_add_f32_e32 v48, v48, v0
	v_add_f32_e32 v49, v49, v1
	v_exp_f32_e32 v233, v51
	v_add_f32_e32 v51, v184, v49
	v_cndmask_b32_e32 v0, 0, v0, vcc
	v_add_f32_e32 v0, v0, v51
	v_add_f32_e32 v55, v62, v54
	v_add_f32_e32 v54, v232, v54
	v_add_f32_e32 v51, v59, v0
	v_exp_f32_e32 v232, v54
	v_add_f32_e32 v54, v58, v51
	v_add_f32_e32 v50, v50, v54
	v_add_f32_e32 v50, v56, v50
	v_exp_f32_e32 v237, v50
	v_add_f32_e32 v50, v57, v54
	v_exp_f32_e32 v238, v50
	v_add_f32_e32 v50, v229, v51
	v_pk_add_f32 v[48:49], v[48:49], v[48:49] op_sel:[0,1] op_sel_hi:[1,0]
	v_exp_f32_e32 v229, v50
	v_add_f32_e32 v49, v184, v48
	v_cndmask_b32_e32 v50, 0, v235, vcc
	v_add_f32_e32 v49, v50, v49
	v_add_f32_e32 v50, v227, v49
	v_add_f32_e32 v51, v225, v50
	v_add_f32_e32 v53, v53, v51
	v_add_f32_e32 v51, v75, v51
	v_add_f32_e32 v50, v226, v50
	v_add_f32_e32 v49, v228, v49
	v_mov_b32_e32 v75, v48
	v_exp_f32_e32 v227, v51
	v_exp_f32_e32 v226, v50
	v_exp_f32_e32 v228, v49
	v_add_f32_e32 v50, v70, v68
	v_add_f32_e32 v51, v71, v69
	v_add_f32_e32 v48, v72, v74
	v_add_f32_e32 v49, v73, v75
	v_add_f32_e32 v52, v52, v53
	v_add_f32_e32 v50, v50, v48
	v_add_f32_e32 v51, v51, v49
	ds_bpermute_b32 v48, v180, v50
	v_exp_f32_e32 v225, v52
	v_cndmask_b32_e32 v52, 0, v69, vcc
	v_add_f32_e32 v49, v184, v49
	v_add_f32_e32 v49, v52, v49
	v_add_f32_e32 v52, v224, v49
	v_add_f32_e32 v49, v223, v49
	s_waitcnt lgkmcnt(0)
	v_add_f32_e32 v50, v50, v48
	v_exp_f32_e32 v73, v49
	v_add_f32_e32 v49, v184, v51
	v_cndmask_b32_e32 v48, 0, v48, vcc
	v_add_f32_e32 v53, v222, v52
	v_add_f32_e32 v48, v48, v49
	v_add_f32_e32 v54, v220, v53
	v_add_f32_e32 v52, v221, v52
	v_add_f32_e32 v49, v74, v48
	v_add_f32_e32 v54, v167, v54
	v_exp_f32_e32 v71, v52
	v_add_f32_e32 v52, v72, v49
	v_add_f32_e32 v49, v78, v49
	v_add_f32_e32 v48, v79, v48
	v_add_f32_e32 v167, v50, v51
	v_exp_f32_e32 v74, v49
	v_exp_f32_e32 v75, v48
	v_add_f32_e32 v48, v184, v167
	v_cndmask_b32_e32 v49, 0, v234, vcc
	v_add_f32_e32 v48, v49, v48
	v_add_f32_e32 v49, v218, v48
	v_add_f32_e32 v50, v216, v49
	v_add_f32_e32 v49, v215, v49
	v_add_f32_e32 v48, v217, v48
	v_exp_f32_e32 v78, v49
	v_exp_f32_e32 v79, v48
	v_add_f32_e32 v48, v66, v166
	v_add_f32_e32 v49, v67, v167
	v_add_f32_e32 v53, v219, v53
	v_add_f32_e32 v51, v214, v50
	v_add_f32_e32 v50, v213, v50
	v_add_f32_e32 v14, v14, v48
	v_add_f32_e32 v15, v15, v49
	v_exp_f32_e32 v70, v53
	v_add_f32_e32 v53, v68, v52
	v_add_f32_e32 v52, v77, v52
	v_exp_f32_e32 v77, v50
	v_cndmask_b32_e32 v50, 0, v65, vcc
	ds_bpermute_b32 v48, v180, v14
	v_add_f32_e32 v49, v184, v49
	v_add_f32_e32 v49, v50, v49
	v_add_f32_e32 v51, v212, v51
	v_add_f32_e32 v50, v211, v49
	v_add_f32_e32 v53, v76, v53
	v_exp_f32_e32 v76, v51
	v_add_f32_e32 v51, v209, v50
	v_exp_f32_e32 v72, v52
	v_add_f32_e32 v52, v207, v51
	v_add_f32_e32 v51, v206, v51
	v_exp_f32_e32 v68, v53
	s_waitcnt lgkmcnt(0)
	v_add_f32_e32 v14, v14, v48
	v_exp_f32_e32 v53, v51
	v_add_f32_e32 v51, v184, v15
	v_cndmask_b32_e32 v48, 0, v48, vcc
	v_add_f32_e32 v48, v48, v51
	v_add_f32_e32 v51, v166, v48
	v_add_f32_e32 v61, v61, v55
	v_add_f32_e32 v55, v231, v55
	v_exp_f32_e32 v69, v54
	v_add_f32_e32 v54, v66, v51
	v_exp_f32_e32 v231, v55
	v_add_f32_e32 v55, v64, v54
	v_add_f32_e32 v52, v205, v52
	v_add_f32_e32 v50, v208, v50
	v_add_f32_e32 v49, v210, v49
	v_add_f32_e32 v55, v165, v55
	v_add_f32_e32 v54, v185, v54
	v_add_f32_e32 v51, v186, v51
	v_add_f32_e32 v48, v204, v48
	v_exp_f32_e32 v52, v52
	v_exp_f32_e32 v50, v50
	v_exp_f32_e32 v49, v49
	v_exp_f32_e32 v55, v55
	v_exp_f32_e32 v54, v54
	v_exp_f32_e32 v56, v51
	v_exp_f32_e32 v48, v48
	v_cvt_pk_bf16_f32 v51, v50, v49
	v_cvt_pk_bf16_f32 v50, v52, v53
	v_add_f32_e32 v60, v60, v61
	v_cvt_pk_bf16_f32 v49, v56, v48
	v_cvt_pk_bf16_f32 v48, v55, v54
	ds_read_b128 v[52:55], v155 offset:64512
	ds_read_b128 v[56:59], v155 offset:64544
	v_exp_f32_e32 v236, v60
	s_waitcnt lgkmcnt(1)
	v_mfma_f32_32x32x16_bf16 v[32:47], v[52:55], v[48:51], v[32:47]
	ds_read_b128 v[52:55], v182 offset:59904
	ds_read_b128 v[60:63], v182 offset:59936
	v_add_f32_e32 v0, v230, v0
	v_exp_f32_e32 v0, v0
	v_add_f32_e32 v14, v14, v15
	v_add_f32_e32 v184, v184, v14
	v_cmp_gt_f32_e64 s[2:3], s2, v184
	s_cmp_eq_u64 s[2:3], exec
	s_waitcnt lgkmcnt(1)
	v_mfma_f32_32x32x16_bf16 v[16:31], v[52:55], v[48:51], v[16:31]
	v_cvt_pk_bf16_f32 v51, v74, v75
	v_cvt_pk_bf16_f32 v50, v68, v72
	v_cvt_pk_bf16_f32 v49, v78, v79
	v_cvt_pk_bf16_f32 v48, v76, v77
	s_cselect_b64 s[2:3], -1, 0
	v_cndmask_b32_e64 v64, 0, 1, s[2:3]
	v_mfma_f32_32x32x16_bf16 v[32:47], v[56:59], v[48:51], v[32:47]
	ds_read_b128 v[52:55], v155 offset:64576
	ds_read_b128 v[56:59], v182 offset:59968
	s_waitcnt lgkmcnt(2)
	v_mfma_f32_32x32x16_bf16 v[16:31], v[60:63], v[48:51], v[16:31]
	v_cvt_pk_bf16_f32 v51, v226, v228
	v_cvt_pk_bf16_f32 v50, v225, v227
	v_cvt_pk_bf16_f32 v49, v71, v73
	v_cvt_pk_bf16_f32 v48, v69, v70
	s_waitcnt lgkmcnt(1)
	s_nop 0
	v_mfma_f32_32x32x16_bf16 v[32:47], v[52:55], v[48:51], v[32:47]
	s_waitcnt lgkmcnt(0)
	v_mfma_f32_32x32x16_bf16 v[16:31], v[56:59], v[48:51], v[16:31]
	ds_read_b128 v[52:55], v155 offset:64608
	ds_read_b128 v[56:59], v182 offset:60000
	v_cvt_pk_bf16_f32 v51, v232, v233
	v_cvt_pk_bf16_f32 v50, v236, v231
	v_cvt_pk_bf16_f32 v49, v229, v0
	v_cvt_pk_bf16_f32 v48, v237, v238
	s_waitcnt lgkmcnt(1)
	s_nop 0
	v_mfma_f32_32x32x16_bf16 v[32:47], v[52:55], v[48:51], v[32:47]
	s_waitcnt lgkmcnt(0)
	v_mfma_f32_32x32x16_bf16 v[16:31], v[56:59], v[48:51], v[16:31]
